# wave-uniform i1 round trips (v_cndmask 0/1 + v_cmp_ne) replaced by one s_andn2_b64 at 35 sites
# speedup vs baseline: 1.0031x; 1.0031x over previous
.LBB0_30:
	v_or_b32_e32 v26, s26, v110
	v_mad_i64_i32 v[6:7], s[56:57], v26, s59, v[24:25]
	global_load_dwordx4 v[6:9], v[6:7], off
	s_andn2_b64 vcc, exec, s[48:49]
	v_ashrrev_i32_e32 v27, 31, v26
	v_or_b32_e32 v5, 4, v26
	v_or_b32_e32 v23, 8, v26
	v_or_b32_e32 v32, 12, v26
	v_or_b32_e32 v33, 16, v26
	v_or_b32_e32 v36, 20, v26
	v_or_b32_e32 v37, 24, v26
	v_or_b32_e32 v66, 28, v26
	v_or_b32_e32 v67, 32, v26
	v_or_b32_e32 v70, 36, v26
	v_or_b32_e32 v71, 40, v26
	v_or_b32_e32 v74, 44, v26
	v_or_b32_e32 v75, 48, v26
	v_or_b32_e32 v111, 52, v26
	v_or_b32_e32 v114, 56, v26
	v_or_b32_e32 v115, 60, v26
	v_mad_i64_i32 v[28:29], s[56:57], v5, s59, v[24:25]
	v_mad_i64_i32 v[30:31], s[56:57], v23, s59, v[24:25]
	v_mad_i64_i32 v[34:35], s[56:57], v32, s59, v[24:25]
	v_mad_i64_i32 v[64:65], s[56:57], v33, s59, v[24:25]
	v_mad_i64_i32 v[68:69], s[56:57], v36, s59, v[24:25]
	v_mad_i64_i32 v[72:73], s[56:57], v37, s59, v[24:25]
	v_mad_i64_i32 v[112:113], s[56:57], v66, s59, v[24:25]
	v_lshl_add_u64 v[148:149], v[26:27], 2, s[38:39]
	global_load_dword v166, v[148:149], off
	global_load_dword v168, v[148:149], off offset:16
	global_load_dword v170, v[148:149], off offset:32
	global_load_dword v172, v[148:149], off offset:48
	global_load_dword v174, v[148:149], off offset:64
	global_load_dword v176, v[148:149], off offset:80
	global_load_dword v178, v[148:149], off offset:96
	global_load_dword v180, v[148:149], off offset:112
	global_load_dword v182, v[148:149], off offset:128
	global_load_dword v184, v[148:149], off offset:144
	global_load_dword v186, v[148:149], off offset:160
	global_load_dword v188, v[148:149], off offset:176
	global_load_dword v190, v[148:149], off offset:192
	global_load_dword v192, v[148:149], off offset:208
	global_load_dword v194, v[148:149], off offset:224
	v_mad_i64_i32 v[116:117], s[56:57], v67, s59, v[24:25]
	v_mad_i64_i32 v[120:121], s[56:57], v70, s59, v[24:25]
	v_mad_i64_i32 v[124:125], s[56:57], v71, s59, v[24:25]
	v_mad_i64_i32 v[128:129], s[56:57], v74, s59, v[24:25]
	v_mad_i64_i32 v[132:133], s[56:57], v75, s59, v[24:25]
	v_mad_i64_i32 v[136:137], s[56:57], v111, s59, v[24:25]
	v_mad_i64_i32 v[140:141], s[56:57], v114, s59, v[24:25]
	v_mad_i64_i32 v[144:145], s[56:57], v115, s59, v[24:25]
	s_nop 0
	global_load_dwordx4 v[26:29], v[28:29], off
	s_nop 0
	s_nop 0
	global_load_dwordx4 v[30:33], v[30:31], off
	s_nop 0
	global_load_dwordx4 v[34:37], v[34:35], off
	s_nop 0
	s_nop 0
	global_load_dwordx4 v[64:67], v[64:65], off
	s_nop 0
	global_load_dwordx4 v[68:71], v[68:69], off
	s_nop 0
	s_nop 0
	global_load_dwordx4 v[72:75], v[72:73], off
	s_nop 0
	global_load_dwordx4 v[112:115], v[112:113], off
	s_nop 0
	s_nop 0
	global_load_dwordx4 v[116:119], v[116:117], off
	s_nop 0
	global_load_dwordx4 v[120:123], v[120:121], off
	s_nop 0
	s_nop 0
	global_load_dwordx4 v[124:127], v[124:125], off
	s_nop 0
	global_load_dwordx4 v[128:131], v[128:129], off
	s_nop 0
	s_nop 0
	global_load_dwordx4 v[132:135], v[132:133], off
	s_nop 0
	global_load_dwordx4 v[136:139], v[136:137], off
	s_nop 0
	s_nop 0
	global_load_dwordx4 v[140:143], v[140:141], off
	s_nop 0
	global_load_dwordx4 v[144:147], v[144:145], off
	s_nop 0
	global_load_dword v148, v[148:149], off offset:240
	s_mov_b32 s26, 64
	s_mov_b64 s[48:49], 0
	s_and_b64 vcc, exec, vcc
	s_waitcnt vmcnt(30)
	v_mul_f32_e32 v6, v6, v166
	v_mul_f32_e32 v7, v7, v166
	v_mul_f32_e32 v8, v8, v166
	v_mul_f32_e32 v5, v9, v166
	s_waitcnt vmcnt(15)
	v_mul_f32_e32 v9, v26, v168
	v_mul_f32_e32 v26, v27, v168
	v_mul_f32_e32 v27, v28, v168
	v_mul_f32_e32 v23, v29, v168
	s_waitcnt vmcnt(14)
	v_mul_f32_e32 v28, v30, v170
	v_mul_f32_e32 v29, v31, v170
	v_mul_f32_e32 v30, v32, v170
	v_mul_f32_e32 v31, v33, v170
	s_waitcnt vmcnt(13)
	v_mul_f32_e32 v32, v34, v172
	v_mul_f32_e32 v33, v35, v172
	v_mul_f32_e32 v34, v36, v172
	v_mul_f32_e32 v35, v37, v172
	v_max3_f32 v4, v4, |v6|, |v9|
	v_max3_f32 v3, v3, |v7|, |v26|
	v_max3_f32 v2, v2, |v8|, |v27|
	v_max3_f32 v0, v0, |v5|, |v23|
	s_waitcnt vmcnt(12)
	v_mul_f32_e32 v36, v64, v174
	v_mul_f32_e32 v37, v65, v174
	v_mul_f32_e32 v64, v66, v174
	v_mul_f32_e32 v65, v67, v174
	s_waitcnt vmcnt(11)
	v_mul_f32_e32 v66, v68, v176
	v_mul_f32_e32 v67, v69, v176
	v_mul_f32_e32 v68, v70, v176
	v_mul_f32_e32 v69, v71, v176
	v_max3_f32 v4, v4, |v28|, |v32|
	v_max3_f32 v3, v3, |v29|, |v33|
	v_max3_f32 v2, v2, |v30|, |v34|
	v_max3_f32 v0, v0, |v31|, |v35|
	s_waitcnt vmcnt(10)
	v_mul_f32_e32 v70, v72, v178
	v_mul_f32_e32 v71, v73, v178
	v_mul_f32_e32 v72, v74, v178
	v_mul_f32_e32 v73, v75, v178
	s_waitcnt vmcnt(9)
	v_mul_f32_e32 v74, v112, v180
	v_mul_f32_e32 v75, v113, v180
	v_mul_f32_e32 v111, v114, v180
	v_mul_f32_e32 v112, v115, v180
	v_max3_f32 v4, v4, |v36|, |v66|
	v_max3_f32 v3, v3, |v37|, |v67|
	v_max3_f32 v2, v2, |v64|, |v68|
	v_max3_f32 v0, v0, |v65|, |v69|
	s_waitcnt vmcnt(8)
	v_mul_f32_e32 v113, v116, v182
	v_mul_f32_e32 v114, v117, v182
	v_mul_f32_e32 v115, v118, v182
	v_mul_f32_e32 v116, v119, v182
	s_waitcnt vmcnt(7)
	v_mul_f32_e32 v117, v120, v184
	v_mul_f32_e32 v118, v121, v184
	v_mul_f32_e32 v119, v122, v184
	v_mul_f32_e32 v120, v123, v184
	v_max3_f32 v4, v4, |v70|, |v74|
	v_max3_f32 v3, v3, |v71|, |v75|
	v_max3_f32 v2, v2, |v72|, |v111|
	v_max3_f32 v0, v0, |v73|, |v112|
	s_waitcnt vmcnt(6)
	v_mul_f32_e32 v121, v124, v186
	v_mul_f32_e32 v122, v125, v186
	v_mul_f32_e32 v123, v126, v186
	v_mul_f32_e32 v124, v127, v186
	s_waitcnt vmcnt(5)
	v_mul_f32_e32 v125, v128, v188
	v_mul_f32_e32 v126, v129, v188
	v_mul_f32_e32 v127, v130, v188
	v_mul_f32_e32 v128, v131, v188
	v_max3_f32 v4, v4, |v113|, |v117|
	v_max3_f32 v3, v3, |v114|, |v118|
	v_max3_f32 v2, v2, |v115|, |v119|
	v_max3_f32 v0, v0, |v116|, |v120|
	s_waitcnt vmcnt(4)
	v_mul_f32_e32 v129, v132, v190
	v_mul_f32_e32 v130, v133, v190
	v_mul_f32_e32 v131, v134, v190
	v_mul_f32_e32 v132, v135, v190
	s_waitcnt vmcnt(3)
	v_mul_f32_e32 v133, v136, v192
	v_mul_f32_e32 v134, v137, v192
	v_mul_f32_e32 v135, v138, v192
	v_mul_f32_e32 v136, v139, v192
	v_max3_f32 v4, v4, |v121|, |v125|
	v_max3_f32 v3, v3, |v122|, |v126|
	v_max3_f32 v2, v2, |v123|, |v127|
	v_max3_f32 v0, v0, |v124|, |v128|
	s_waitcnt vmcnt(2)
	v_mul_f32_e32 v137, v140, v194
	v_mul_f32_e32 v138, v141, v194
	v_mul_f32_e32 v139, v142, v194
	v_mul_f32_e32 v140, v143, v194
	s_waitcnt vmcnt(0)
	v_mul_f32_e32 v141, v144, v148
	v_mul_f32_e32 v142, v145, v148
	v_mul_f32_e32 v143, v146, v148
	v_mul_f32_e32 v144, v147, v148
	v_max3_f32 v4, v4, |v129|, |v133|
	v_max3_f32 v3, v3, |v130|, |v134|
	v_max3_f32 v2, v2, |v131|, |v135|
	v_max3_f32 v0, v0, |v132|, |v136|
	v_max3_f32 v4, v4, |v137|, |v141|
	v_max3_f32 v3, v3, |v138|, |v142|
	v_max3_f32 v2, v2, |v139|, |v143|
	v_max3_f32 v0, v0, |v140|, |v144|
	s_cbranch_vccz .LBB0_30
	v_and_b32_e32 v6, 64, v88
	v_xor_b32_e32 v5, 16, v88
	v_add_u32_e32 v6, 64, v6
	v_cmp_lt_i32_e32 vcc, v5, v6
	s_nop 1
	v_cndmask_b32_e32 v5, v88, v5, vcc
	v_lshlrev_b32_e32 v7, 2, v5
	ds_bpermute_b32 v8, v7, v4
	v_xor_b32_e32 v5, 32, v88
	v_cmp_lt_i32_e32 vcc, v5, v6
	ds_bpermute_b32 v6, v7, v3
	ds_bpermute_b32 v23, v7, v0
	v_cndmask_b32_e32 v5, v88, v5, vcc
	v_lshlrev_b32_e32 v9, 2, v5
	s_waitcnt lgkmcnt(2)
	v_max_f32_e32 v5, v8, v8
	ds_bpermute_b32 v8, v7, v2
	v_max_f32_e32 v4, v4, v4
	s_waitcnt lgkmcnt(2)
	v_max_f32_e32 v6, v6, v6
	v_max_f32_e32 v3, v3, v3
	v_max_f32_e32 v2, v2, v2
	s_waitcnt lgkmcnt(0)
	v_max_f32_e32 v7, v8, v8
	v_max_f32_e32 v8, v23, v23
	v_max_f32_e32 v0, v0, v0
	v_max_f32_e32 v4, v4, v5
	v_max_f32_e32 v3, v3, v6
	v_max_f32_e32 v2, v2, v7
	v_max_f32_e32 v0, v0, v8
	ds_bpermute_b32 v5, v9, v4
	ds_bpermute_b32 v6, v9, v3
	ds_bpermute_b32 v7, v9, v2
	ds_bpermute_b32 v8, v9, v0
	s_and_saveexec_b64 s[48:49], s[2:3]
	s_cbranch_execz .LBB0_33
	s_waitcnt lgkmcnt(0)
	v_max_f32_e32 v8, v8, v8
	v_max_f32_e32 v0, v0, v0
	v_max_f32_e32 v9, v0, v8
	v_max_f32_e32 v0, v7, v7
	v_max_f32_e32 v2, v2, v2
	v_max_f32_e32 v8, v2, v0
	v_max_f32_e32 v0, v6, v6
	v_max_f32_e32 v2, v3, v3
	v_max_f32_e32 v7, v2, v0
	v_max_f32_e32 v0, v5, v5
	v_max_f32_e32 v2, v4, v4
	v_max_f32_e32 v6, v2, v0
	v_add_u32_e32 v0, s6, v60
	ds_write_b128 v0, v[6:9]

.LBB0_40:
	v_or_b32_e32 v26, s7, v110
	v_mad_i64_i32 v[6:7], s[56:57], v26, s22, v[24:25]
	global_load_dwordx4 v[6:9], v[6:7], off
	s_andn2_b64 vcc, exec, s[48:49]
	v_ashrrev_i32_e32 v27, 31, v26
	v_or_b32_e32 v5, 4, v26
	v_or_b32_e32 v23, 8, v26
	v_or_b32_e32 v32, 12, v26
	v_or_b32_e32 v33, 16, v26
	v_or_b32_e32 v36, 20, v26
	v_or_b32_e32 v37, 24, v26
	v_or_b32_e32 v66, 28, v26
	v_or_b32_e32 v67, 32, v26
	v_or_b32_e32 v70, 36, v26
	v_or_b32_e32 v71, 40, v26
	v_or_b32_e32 v74, 44, v26
	v_or_b32_e32 v75, 48, v26
	v_or_b32_e32 v111, 52, v26
	v_or_b32_e32 v114, 56, v26
	v_or_b32_e32 v115, 60, v26
	v_mad_i64_i32 v[28:29], s[56:57], v5, s22, v[24:25]
	v_mad_i64_i32 v[30:31], s[56:57], v23, s22, v[24:25]
	v_mad_i64_i32 v[34:35], s[56:57], v32, s22, v[24:25]
	v_mad_i64_i32 v[64:65], s[56:57], v33, s22, v[24:25]
	v_mad_i64_i32 v[68:69], s[56:57], v36, s22, v[24:25]
	v_mad_i64_i32 v[72:73], s[56:57], v37, s22, v[24:25]
	v_mad_i64_i32 v[112:113], s[56:57], v66, s22, v[24:25]
	v_lshl_add_u64 v[148:149], v[26:27], 2, s[10:11]
	global_load_dword v166, v[148:149], off
	global_load_dword v168, v[148:149], off offset:16
	global_load_dword v170, v[148:149], off offset:32
	global_load_dword v172, v[148:149], off offset:48
	global_load_dword v174, v[148:149], off offset:64
	global_load_dword v176, v[148:149], off offset:80
	global_load_dword v178, v[148:149], off offset:96
	global_load_dword v180, v[148:149], off offset:112
	global_load_dword v182, v[148:149], off offset:128
	global_load_dword v184, v[148:149], off offset:144
	global_load_dword v186, v[148:149], off offset:160
	global_load_dword v188, v[148:149], off offset:176
	global_load_dword v190, v[148:149], off offset:192
	global_load_dword v192, v[148:149], off offset:208
	global_load_dword v194, v[148:149], off offset:224
	v_mad_i64_i32 v[116:117], s[56:57], v67, s22, v[24:25]
	v_mad_i64_i32 v[120:121], s[56:57], v70, s22, v[24:25]
	v_mad_i64_i32 v[124:125], s[56:57], v71, s22, v[24:25]
	v_mad_i64_i32 v[128:129], s[56:57], v74, s22, v[24:25]
	v_mad_i64_i32 v[132:133], s[56:57], v75, s22, v[24:25]
	v_mad_i64_i32 v[136:137], s[56:57], v111, s22, v[24:25]
	v_mad_i64_i32 v[140:141], s[56:57], v114, s22, v[24:25]
	v_mad_i64_i32 v[144:145], s[56:57], v115, s22, v[24:25]
	s_nop 0
	global_load_dwordx4 v[26:29], v[28:29], off
	s_nop 0
	s_nop 0
	global_load_dwordx4 v[30:33], v[30:31], off
	s_nop 0
	global_load_dwordx4 v[34:37], v[34:35], off
	s_nop 0
	s_nop 0
	global_load_dwordx4 v[64:67], v[64:65], off
	s_nop 0
	global_load_dwordx4 v[68:71], v[68:69], off
	s_nop 0
	s_nop 0
	global_load_dwordx4 v[72:75], v[72:73], off
	s_nop 0
	global_load_dwordx4 v[112:115], v[112:113], off
	s_nop 0
	s_nop 0
	global_load_dwordx4 v[116:119], v[116:117], off
	s_nop 0
	global_load_dwordx4 v[120:123], v[120:121], off
	s_nop 0
	s_nop 0
	global_load_dwordx4 v[124:127], v[124:125], off
	s_nop 0
	global_load_dwordx4 v[128:131], v[128:129], off
	s_nop 0
	s_nop 0
	global_load_dwordx4 v[132:135], v[132:133], off
	s_nop 0
	global_load_dwordx4 v[136:139], v[136:137], off
	s_nop 0
	s_nop 0
	global_load_dwordx4 v[140:143], v[140:141], off
	s_nop 0
	global_load_dwordx4 v[144:147], v[144:145], off
	s_nop 0
	global_load_dword v148, v[148:149], off offset:240
	s_mov_b32 s7, 64
	s_mov_b64 s[48:49], 0
	s_and_b64 vcc, exec, vcc
	s_waitcnt vmcnt(30)
	v_mul_f32_e32 v6, v6, v166
	v_mul_f32_e32 v7, v7, v166
	v_mul_f32_e32 v8, v8, v166
	v_mul_f32_e32 v5, v9, v166
	s_waitcnt vmcnt(15)
	v_mul_f32_e32 v9, v26, v168
	v_mul_f32_e32 v26, v27, v168
	v_mul_f32_e32 v27, v28, v168
	v_mul_f32_e32 v23, v29, v168
	s_waitcnt vmcnt(14)
	v_mul_f32_e32 v28, v30, v170
	v_mul_f32_e32 v29, v31, v170
	v_mul_f32_e32 v30, v32, v170
	v_mul_f32_e32 v31, v33, v170
	s_waitcnt vmcnt(13)
	v_mul_f32_e32 v32, v34, v172
	v_mul_f32_e32 v33, v35, v172
	v_mul_f32_e32 v34, v36, v172
	v_mul_f32_e32 v35, v37, v172
	v_max3_f32 v4, v4, |v6|, |v9|
	v_max3_f32 v3, v3, |v7|, |v26|
	v_max3_f32 v2, v2, |v8|, |v27|
	v_max3_f32 v0, v0, |v5|, |v23|
	s_waitcnt vmcnt(12)
	v_mul_f32_e32 v36, v64, v174
	v_mul_f32_e32 v37, v65, v174
	v_mul_f32_e32 v64, v66, v174
	v_mul_f32_e32 v65, v67, v174
	s_waitcnt vmcnt(11)
	v_mul_f32_e32 v66, v68, v176
	v_mul_f32_e32 v67, v69, v176
	v_mul_f32_e32 v68, v70, v176
	v_mul_f32_e32 v69, v71, v176
	v_max3_f32 v4, v4, |v28|, |v32|
	v_max3_f32 v3, v3, |v29|, |v33|
	v_max3_f32 v2, v2, |v30|, |v34|
	v_max3_f32 v0, v0, |v31|, |v35|
	s_waitcnt vmcnt(10)
	v_mul_f32_e32 v70, v72, v178
	v_mul_f32_e32 v71, v73, v178
	v_mul_f32_e32 v72, v74, v178
	v_mul_f32_e32 v73, v75, v178
	s_waitcnt vmcnt(9)
	v_mul_f32_e32 v74, v112, v180
	v_mul_f32_e32 v75, v113, v180
	v_mul_f32_e32 v111, v114, v180
	v_mul_f32_e32 v112, v115, v180
	v_max3_f32 v4, v4, |v36|, |v66|
	v_max3_f32 v3, v3, |v37|, |v67|
	v_max3_f32 v2, v2, |v64|, |v68|
	v_max3_f32 v0, v0, |v65|, |v69|
	s_waitcnt vmcnt(8)
	v_mul_f32_e32 v113, v116, v182
	v_mul_f32_e32 v114, v117, v182
	v_mul_f32_e32 v115, v118, v182
	v_mul_f32_e32 v116, v119, v182
	s_waitcnt vmcnt(7)
	v_mul_f32_e32 v117, v120, v184
	v_mul_f32_e32 v118, v121, v184
	v_mul_f32_e32 v119, v122, v184
	v_mul_f32_e32 v120, v123, v184
	v_max3_f32 v4, v4, |v70|, |v74|
	v_max3_f32 v3, v3, |v71|, |v75|
	v_max3_f32 v2, v2, |v72|, |v111|
	v_max3_f32 v0, v0, |v73|, |v112|
	s_waitcnt vmcnt(6)
	v_mul_f32_e32 v121, v124, v186
	v_mul_f32_e32 v122, v125, v186
	v_mul_f32_e32 v123, v126, v186
	v_mul_f32_e32 v124, v127, v186
	s_waitcnt vmcnt(5)
	v_mul_f32_e32 v125, v128, v188
	v_mul_f32_e32 v126, v129, v188
	v_mul_f32_e32 v127, v130, v188
	v_mul_f32_e32 v128, v131, v188
	v_max3_f32 v4, v4, |v113|, |v117|
	v_max3_f32 v3, v3, |v114|, |v118|
	v_max3_f32 v2, v2, |v115|, |v119|
	v_max3_f32 v0, v0, |v116|, |v120|
	s_waitcnt vmcnt(4)
	v_mul_f32_e32 v129, v132, v190
	v_mul_f32_e32 v130, v133, v190
	v_mul_f32_e32 v131, v134, v190
	v_mul_f32_e32 v132, v135, v190
	s_waitcnt vmcnt(3)
	v_mul_f32_e32 v133, v136, v192
	v_mul_f32_e32 v134, v137, v192
	v_mul_f32_e32 v135, v138, v192
	v_mul_f32_e32 v136, v139, v192
	v_max3_f32 v4, v4, |v121|, |v125|
	v_max3_f32 v3, v3, |v122|, |v126|
	v_max3_f32 v2, v2, |v123|, |v127|
	v_max3_f32 v0, v0, |v124|, |v128|
	s_waitcnt vmcnt(2)
	v_mul_f32_e32 v137, v140, v194
	v_mul_f32_e32 v138, v141, v194
	v_mul_f32_e32 v139, v142, v194
	v_mul_f32_e32 v140, v143, v194
	s_waitcnt vmcnt(0)
	v_mul_f32_e32 v141, v144, v148
	v_mul_f32_e32 v142, v145, v148
	v_mul_f32_e32 v143, v146, v148
	v_mul_f32_e32 v144, v147, v148
	v_max3_f32 v4, v4, |v129|, |v133|
	v_max3_f32 v3, v3, |v130|, |v134|
	v_max3_f32 v2, v2, |v131|, |v135|
	v_max3_f32 v0, v0, |v132|, |v136|
	v_max3_f32 v4, v4, |v137|, |v141|
	v_max3_f32 v3, v3, |v138|, |v142|
	v_max3_f32 v2, v2, |v139|, |v143|
	v_max3_f32 v0, v0, |v140|, |v144|
	s_cbranch_vccz .LBB0_40
	v_and_b32_e32 v6, 64, v88
	v_xor_b32_e32 v5, 16, v88
	v_add_u32_e32 v6, 64, v6
	v_cmp_lt_i32_e32 vcc, v5, v6
	s_nop 1
	v_cndmask_b32_e32 v5, v88, v5, vcc
	v_lshlrev_b32_e32 v7, 2, v5
	ds_bpermute_b32 v8, v7, v4
	v_xor_b32_e32 v5, 32, v88
	v_cmp_lt_i32_e32 vcc, v5, v6
	ds_bpermute_b32 v6, v7, v3
	ds_bpermute_b32 v23, v7, v0
	v_cndmask_b32_e32 v5, v88, v5, vcc
	v_lshlrev_b32_e32 v9, 2, v5
	s_waitcnt lgkmcnt(2)
	v_max_f32_e32 v5, v8, v8
	ds_bpermute_b32 v8, v7, v2
	v_max_f32_e32 v4, v4, v4
	s_waitcnt lgkmcnt(2)
	v_max_f32_e32 v6, v6, v6
	v_max_f32_e32 v3, v3, v3
	v_max_f32_e32 v2, v2, v2
	s_waitcnt lgkmcnt(0)
	v_max_f32_e32 v7, v8, v8
	v_max_f32_e32 v8, v23, v23
	v_max_f32_e32 v0, v0, v0
	v_max_f32_e32 v4, v4, v5
	v_max_f32_e32 v3, v3, v6
	v_max_f32_e32 v2, v2, v7
	v_max_f32_e32 v0, v0, v8
	ds_bpermute_b32 v5, v9, v4
	ds_bpermute_b32 v6, v9, v3
	ds_bpermute_b32 v7, v9, v2
	ds_bpermute_b32 v8, v9, v0
	s_and_saveexec_b64 s[48:49], s[2:3]
	s_cbranch_execz .LBB0_43
	s_waitcnt lgkmcnt(0)
	v_max_f32_e32 v8, v8, v8
	v_max_f32_e32 v0, v0, v0
	v_max_f32_e32 v9, v0, v8
	v_max_f32_e32 v0, v7, v7
	v_max_f32_e32 v2, v2, v2
	v_max_f32_e32 v8, v2, v0
	v_max_f32_e32 v0, v6, v6
	v_max_f32_e32 v2, v3, v3
	v_max_f32_e32 v7, v2, v0
	v_max_f32_e32 v0, v5, v5
	v_max_f32_e32 v2, v4, v4
	v_max_f32_e32 v6, v2, v0
	v_add_u32_e32 v0, s6, v60
	ds_write_b128 v0, v[6:9]

.LBB0_64:
	v_or_b32_e32 v2, s9, v110
	v_mad_i64_i32 v[8:9], s[56:57], v2, s22, v[24:25]
	global_load_dwordx4 v[26:29], v[8:9], off
	s_andn2_b64 vcc, exec, s[48:49]
	v_ashrrev_i32_e32 v3, 31, v2
	v_or_b32_e32 v7, 4, v2
	v_or_b32_e32 v23, 8, v2
	v_or_b32_e32 v30, 12, v2
	v_or_b32_e32 v31, 16, v2
	v_or_b32_e32 v32, 20, v2
	v_or_b32_e32 v33, 24, v2
	v_or_b32_e32 v36, 28, v2
	v_or_b32_e32 v37, 32, v2
	v_or_b32_e32 v66, 36, v2
	v_or_b32_e32 v67, 40, v2
	v_or_b32_e32 v70, 44, v2
	v_or_b32_e32 v71, 48, v2
	v_or_b32_e32 v74, 52, v2
	v_or_b32_e32 v75, 56, v2
	v_or_b32_e32 v111, 60, v2
	v_mad_i64_i32 v[8:9], s[56:57], v7, s22, v[24:25]
	v_mad_i64_i32 v[34:35], s[56:57], v23, s22, v[24:25]
	v_mad_i64_i32 v[64:65], s[56:57], v30, s22, v[24:25]
	v_mad_i64_i32 v[68:69], s[56:57], v31, s22, v[24:25]
	v_mad_i64_i32 v[72:73], s[56:57], v32, s22, v[24:25]
	v_mad_i64_i32 v[112:113], s[56:57], v33, s22, v[24:25]
	v_mad_i64_i32 v[116:117], s[56:57], v36, s22, v[24:25]
	v_lshl_add_u64 v[2:3], v[2:3], 2, s[10:11]
	global_load_dword v166, v[2:3], off
	global_load_dword v168, v[2:3], off offset:16
	global_load_dword v170, v[2:3], off offset:32
	global_load_dword v172, v[2:3], off offset:48
	global_load_dword v174, v[2:3], off offset:64
	global_load_dword v176, v[2:3], off offset:80
	global_load_dword v178, v[2:3], off offset:96
	global_load_dword v180, v[2:3], off offset:112
	global_load_dword v182, v[2:3], off offset:128
	global_load_dword v184, v[2:3], off offset:144
	global_load_dword v186, v[2:3], off offset:160
	global_load_dword v188, v[2:3], off offset:176
	global_load_dword v190, v[2:3], off offset:192
	global_load_dword v192, v[2:3], off offset:208
	global_load_dword v194, v[2:3], off offset:224
	v_mad_i64_i32 v[120:121], s[56:57], v37, s22, v[24:25]
	v_mad_i64_i32 v[124:125], s[56:57], v66, s22, v[24:25]
	v_mad_i64_i32 v[128:129], s[56:57], v67, s22, v[24:25]
	v_mad_i64_i32 v[132:133], s[56:57], v70, s22, v[24:25]
	v_mad_i64_i32 v[136:137], s[56:57], v71, s22, v[24:25]
	v_mad_i64_i32 v[140:141], s[56:57], v74, s22, v[24:25]
	v_mad_i64_i32 v[144:145], s[56:57], v75, s22, v[24:25]
	v_mad_i64_i32 v[148:149], s[56:57], v111, s22, v[24:25]
	global_load_dwordx4 v[30:33], v[8:9], off
	s_nop 0
	s_nop 0
	global_load_dwordx4 v[34:37], v[34:35], off
	s_nop 0
	global_load_dwordx4 v[64:67], v[64:65], off
	s_nop 0
	s_nop 0
	global_load_dwordx4 v[68:71], v[68:69], off
	s_nop 0
	global_load_dwordx4 v[72:75], v[72:73], off
	s_nop 0
	s_nop 0
	global_load_dwordx4 v[112:115], v[112:113], off
	s_nop 0
	global_load_dwordx4 v[116:119], v[116:117], off
	s_nop 0
	s_nop 0
	global_load_dwordx4 v[120:123], v[120:121], off
	s_nop 0
	global_load_dwordx4 v[124:127], v[124:125], off
	s_nop 0
	s_nop 0
	global_load_dwordx4 v[128:131], v[128:129], off
	s_nop 0
	global_load_dwordx4 v[132:135], v[132:133], off
	s_nop 0
	s_nop 0
	global_load_dwordx4 v[136:139], v[136:137], off
	s_nop 0
	global_load_dwordx4 v[140:143], v[140:141], off
	s_nop 0
	s_nop 0
	global_load_dwordx4 v[144:147], v[144:145], off
	s_nop 0
	global_load_dwordx4 v[148:151], v[148:149], off
	s_nop 0
	global_load_dword v2, v[2:3], off offset:240
	s_mov_b32 s9, 64
	s_mov_b64 s[48:49], 0
	s_and_b64 vcc, exec, vcc
	s_waitcnt vmcnt(30)
	v_mul_f32_e32 v3, v26, v166
	v_mul_f32_e32 v26, v27, v166
	v_mul_f32_e32 v27, v28, v166
	v_mul_f32_e32 v7, v29, v166
	s_waitcnt vmcnt(15)
	v_mul_f32_e32 v28, v30, v168
	v_mul_f32_e32 v29, v31, v168
	v_mul_f32_e32 v30, v32, v168
	v_mul_f32_e32 v8, v33, v168
	s_waitcnt vmcnt(14)
	v_mul_f32_e32 v31, v34, v170
	v_mul_f32_e32 v32, v35, v170
	v_mul_f32_e32 v33, v36, v170
	v_mul_f32_e32 v9, v37, v170
	s_waitcnt vmcnt(13)
	v_mul_f32_e32 v34, v64, v172
	v_mul_f32_e32 v35, v65, v172
	v_mul_f32_e32 v36, v66, v172
	v_mul_f32_e32 v23, v67, v172
	v_max3_f32 v3, v6, |v3|, |v28|
	v_max3_f32 v5, v5, |v26|, |v29|
	v_max3_f32 v4, v4, |v27|, |v30|
	v_max3_f32 v0, v0, |v7|, |v8|
	s_waitcnt vmcnt(12)
	v_mul_f32_e32 v37, v68, v174
	v_mul_f32_e32 v64, v69, v174
	v_mul_f32_e32 v65, v70, v174
	v_mul_f32_e32 v66, v71, v174
	s_waitcnt vmcnt(11)
	v_mul_f32_e32 v67, v72, v176
	v_mul_f32_e32 v68, v73, v176
	v_mul_f32_e32 v69, v74, v176
	v_mul_f32_e32 v70, v75, v176
	v_max3_f32 v3, v3, |v31|, |v34|
	v_max3_f32 v5, v5, |v32|, |v35|
	v_max3_f32 v4, v4, |v33|, |v36|
	v_max3_f32 v0, v0, |v9|, |v23|
	s_waitcnt vmcnt(10)
	v_mul_f32_e32 v71, v112, v178
	v_mul_f32_e32 v72, v113, v178
	v_mul_f32_e32 v73, v114, v178
	v_mul_f32_e32 v74, v115, v178
	s_waitcnt vmcnt(9)
	v_mul_f32_e32 v75, v116, v180
	v_mul_f32_e32 v111, v117, v180
	v_mul_f32_e32 v112, v118, v180
	v_mul_f32_e32 v113, v119, v180
	v_max3_f32 v3, v3, |v37|, |v67|
	v_max3_f32 v5, v5, |v64|, |v68|
	v_max3_f32 v4, v4, |v65|, |v69|
	v_max3_f32 v0, v0, |v66|, |v70|
	s_waitcnt vmcnt(8)
	v_mul_f32_e32 v114, v120, v182
	v_mul_f32_e32 v115, v121, v182
	v_mul_f32_e32 v116, v122, v182
	v_mul_f32_e32 v117, v123, v182
	s_waitcnt vmcnt(7)
	v_mul_f32_e32 v118, v124, v184
	v_mul_f32_e32 v119, v125, v184
	v_mul_f32_e32 v120, v126, v184
	v_mul_f32_e32 v121, v127, v184
	v_max3_f32 v3, v3, |v71|, |v75|
	v_max3_f32 v5, v5, |v72|, |v111|
	v_max3_f32 v4, v4, |v73|, |v112|
	v_max3_f32 v0, v0, |v74|, |v113|
	s_waitcnt vmcnt(6)
	v_mul_f32_e32 v122, v128, v186
	v_mul_f32_e32 v123, v129, v186
	v_mul_f32_e32 v124, v130, v186
	v_mul_f32_e32 v125, v131, v186
	s_waitcnt vmcnt(5)
	v_mul_f32_e32 v126, v132, v188
	v_mul_f32_e32 v127, v133, v188
	v_mul_f32_e32 v128, v134, v188
	v_mul_f32_e32 v129, v135, v188
	v_max3_f32 v3, v3, |v114|, |v118|
	v_max3_f32 v5, v5, |v115|, |v119|
	v_max3_f32 v4, v4, |v116|, |v120|
	v_max3_f32 v0, v0, |v117|, |v121|
	s_waitcnt vmcnt(4)
	v_mul_f32_e32 v130, v136, v190
	v_mul_f32_e32 v131, v137, v190
	v_mul_f32_e32 v132, v138, v190
	v_mul_f32_e32 v133, v139, v190
	s_waitcnt vmcnt(3)
	v_mul_f32_e32 v134, v140, v192
	v_mul_f32_e32 v135, v141, v192
	v_mul_f32_e32 v136, v142, v192
	v_mul_f32_e32 v137, v143, v192
	v_max3_f32 v3, v3, |v122|, |v126|
	v_max3_f32 v5, v5, |v123|, |v127|
	v_max3_f32 v4, v4, |v124|, |v128|
	v_max3_f32 v0, v0, |v125|, |v129|
	s_waitcnt vmcnt(2)
	v_mul_f32_e32 v138, v144, v194
	v_mul_f32_e32 v139, v145, v194
	v_mul_f32_e32 v140, v146, v194
	v_mul_f32_e32 v141, v147, v194
	s_waitcnt vmcnt(0)
	v_mul_f32_e32 v142, v148, v2
	v_mul_f32_e32 v143, v149, v2
	v_mul_f32_e32 v144, v150, v2
	v_mul_f32_e32 v2, v151, v2
	v_max3_f32 v3, v3, |v130|, |v134|
	v_max3_f32 v5, v5, |v131|, |v135|
	v_max3_f32 v4, v4, |v132|, |v136|
	v_max3_f32 v0, v0, |v133|, |v137|
	v_max3_f32 v6, v3, |v138|, |v142|
	v_max3_f32 v5, v5, |v139|, |v143|
	v_max3_f32 v4, v4, |v140|, |v144|
	v_max3_f32 v0, v0, |v141|, |v2|
	s_cbranch_vccz .LBB0_64
	v_and_b32_e32 v3, 64, v88
	v_xor_b32_e32 v2, 16, v88
	v_add_u32_e32 v3, 64, v3
	v_cmp_lt_i32_e32 vcc, v2, v3
	s_nop 1
	v_cndmask_b32_e32 v2, v88, v2, vcc
	v_lshlrev_b32_e32 v7, 2, v2
	ds_bpermute_b32 v8, v7, v6
	ds_bpermute_b32 v23, v7, v5
	v_xor_b32_e32 v2, 32, v88
	v_cmp_lt_i32_e32 vcc, v2, v3
	v_max_f32_e32 v3, v6, v6
	v_max_f32_e32 v5, v5, v5
	v_cndmask_b32_e32 v2, v88, v2, vcc
	v_lshlrev_b32_e32 v9, 2, v2
	s_waitcnt lgkmcnt(1)
	v_max_f32_e32 v2, v8, v8
	s_waitcnt lgkmcnt(0)
	v_max_f32_e32 v6, v23, v23
	ds_bpermute_b32 v8, v7, v4
	ds_bpermute_b32 v23, v7, v0
	v_max_f32_e32 v4, v4, v4
	v_max_f32_e32 v0, v0, v0
	v_max_f32_e32 v2, v3, v2
	s_waitcnt lgkmcnt(1)
	v_max_f32_e32 v7, v8, v8
	s_waitcnt lgkmcnt(0)
	v_max_f32_e32 v8, v23, v23
	v_max_f32_e32 v5, v5, v6
	v_max_f32_e32 v4, v4, v7
	v_max_f32_e32 v0, v0, v8
	ds_bpermute_b32 v3, v9, v2
	ds_bpermute_b32 v6, v9, v5
	ds_bpermute_b32 v7, v9, v4
	ds_bpermute_b32 v8, v9, v0
	s_and_saveexec_b64 s[48:49], s[2:3]
	s_cbranch_execz .LBB0_67
	s_waitcnt lgkmcnt(0)
	v_max_f32_e32 v8, v8, v8
	v_max_f32_e32 v0, v0, v0
	v_max_f32_e32 v9, v0, v8
	v_max_f32_e32 v0, v7, v7
	v_max_f32_e32 v4, v4, v4
	v_max_f32_e32 v8, v4, v0
	v_max_f32_e32 v0, v6, v6
	v_max_f32_e32 v4, v5, v5
	v_max_f32_e32 v7, v4, v0
	v_max_f32_e32 v0, v3, v3
	v_max_f32_e32 v2, v2, v2
	v_max_f32_e32 v6, v2, v0
	v_add_u32_e32 v0, s6, v60
	ds_write_b128 v0, v[6:9]

.LBB0_103:
	s_lshl_b32 s3, s50, 10
	s_sub_i32 s48, s26, s3
	s_ashr_i32 s3, s2, 31
	v_add_u32_e32 v34, s48, v62
	v_lshl_add_u64 v[2:3], s[2:3], 2, v[72:73]
	v_mad_i64_i32 v[4:5], s[2:3], v34, s22, v[2:3]
	s_mul_i32 s2, s50, 0xfe500000
	s_nop 0
	v_add_u32_e32 v6, s2, v112
	v_ashrrev_i32_e32 v7, 31, v6
	v_lshl_add_u64 v[78:79], v[2:3], 0, v[6:7]
	s_mov_b32 s2, 0x1b000
	v_add_co_u32_e32 v2, vcc, s2, v78
	s_mov_b32 s2, 0x36000
	s_nop 0
	v_addc_co_u32_e32 v3, vcc, 0, v79, vcc
	global_load_dwordx4 v[26:29], v[4:5], off nt
	global_load_dwordx4 v[30:33], v[2:3], off nt
	v_add_co_u32_e32 v2, vcc, s2, v78
	s_mov_b32 s2, 0x51000
	s_nop 0
	v_addc_co_u32_e32 v3, vcc, 0, v79, vcc
	v_add_co_u32_e32 v4, vcc, s2, v78
	s_mov_b32 s2, 0x6c000
	s_nop 0
	v_addc_co_u32_e32 v5, vcc, 0, v79, vcc
	global_load_dwordx4 v[18:21], v[2:3], off nt
	global_load_dwordx4 v[22:25], v[4:5], off nt
	v_add_co_u32_e32 v2, vcc, s2, v78
	v_readlane_b32 s54, v254, 19
	s_nop 0
	v_addc_co_u32_e32 v3, vcc, 0, v79, vcc
	v_add_co_u32_e32 v4, vcc, 0x87000, v78
	v_readlane_b32 s55, v254, 20
	s_nop 0
	v_addc_co_u32_e32 v5, vcc, 0, v79, vcc
	global_load_dwordx4 v[10:13], v[2:3], off nt
	global_load_dwordx4 v[14:17], v[4:5], off nt
	v_add_co_u32_e32 v2, vcc, 0xa2000, v78
	s_nop 0
	s_nop 0
	v_addc_co_u32_e32 v3, vcc, 0, v79, vcc
	v_add_co_u32_e32 v6, vcc, 0xbd000, v78
	s_andn2_b64 s[2:3], exec, s[54:55]
	s_nop 0
	v_addc_co_u32_e32 v7, vcc, 0, v79, vcc
	global_load_dwordx4 v[2:5], v[2:3], off nt
	s_nop 0
	global_load_dwordx4 v[6:9], v[6:7], off nt
	s_andn2_b64 vcc, exec, s[54:55]
	s_cbranch_vccnz .LBB0_126
	v_ashrrev_i32_e32 v35, 31, v34
	s_ashr_i32 s49, s48, 31
	v_lshl_add_u64 v[34:35], v[34:35], 2, s[10:11]
	v_lshl_add_u64 v[36:37], s[48:49], 0, v[62:63]
	global_load_dword v34, v[34:35], off
	v_lshl_add_u64 v[36:37], v[36:37], 2, s[10:11]
	global_load_dword v118, v[36:37], off offset:16
	s_waitcnt vmcnt(1)
	v_pk_mul_f32 v[36:37], v[28:29], v[34:35] op_sel_hi:[1,0]
	v_pk_mul_f32 v[34:35], v[26:27], v[34:35] op_sel_hi:[1,0]
	ds_write2_b32 v110, v34, v35 offset1:1
	ds_write2_b32 v110, v36, v37 offset0:2 offset1:3
	s_waitcnt vmcnt(0)
	v_pk_mul_f32 v[36:37], v[32:33], v[118:119] op_sel_hi:[1,0]
	v_pk_mul_f32 v[34:35], v[30:31], v[118:119] op_sel_hi:[1,0]
	s_cbranch_execnz .LBB0_106

.LBB0_283:
	s_barrier
	s_load_dwordx2 s[4:5], s[92:93], 0x108
	s_waitcnt lgkmcnt(0)
	s_cmp_lt_i32 s4, 2
	s_cselect_b64 s[0:1], -1, 0
	s_cmp_gt_i32 s5, 1
	s_cselect_b64 s[2:3], -1, 0
	s_and_b64 s[0:1], s[0:1], s[2:3]
	s_andn2_b64 vcc, exec, s[0:1]
	s_andn2_b64 s[0:1], exec, s[52:53]
	s_nop 1
	v_writelane_b32 v254, s0, 58
	s_nop 1
	v_writelane_b32 v254, s1, 59
	s_cbranch_vccnz .LBB0_609
	s_load_dwordx2 s[4:5], s[92:93], 0x100
	v_readlane_b32 s0, v254, 58
	v_readlane_b32 s1, v254, 59
	s_and_b64 vcc, exec, s[0:1]
	s_cbranch_vccnz .LBB0_361
	s_load_dword s2, s[92:93], 0x114
	v_mbcnt_lo_u32_b32 v0, -1, 0
	v_mbcnt_hi_u32_b32 v41, -1, v0
	v_and_b32_e32 v0, 64, v41
	s_mul_i32 s0, s46, 24
	s_waitcnt lgkmcnt(0)
	s_cmp_eq_u32 s2, 16
	s_mov_b32 s1, 0
	s_cselect_b32 s2, 2, 1
	s_lshl_b32 s3, s46, 3
	s_lshl_b32 s28, s46, 4
	v_mov_b32_e32 v1, 0
	s_mov_b64 s[8:9], 0x2700000
	s_mov_b64 s[10:11], 0xef00000
	s_mov_b32 s29, 0x42fe0000
	s_mov_b32 s30, 0xc2fe0000
	s_mov_b32 s31, 0xc0c0400
	s_mov_b32 s33, 0x5040100
	v_mov_b32_e32 v40, 0x358637bd
	s_mov_b32 s34, 0x800000
	v_add_u32_e32 v42, 64, v0
	v_xor_b32_e32 v43, 32, v41
	v_xor_b32_e32 v44, 16, v41
	v_xor_b32_e32 v45, 8, v41
	v_xor_b32_e32 v46, 4, v41
	v_xor_b32_e32 v47, 2, v41
	v_xor_b32_e32 v48, 1, v41
	v_mov_b32_e32 v49, 0x42fe0000
	s_branch .LBB0_287

.LBB0_429:
	v_pk_mul_f32 v[104:105], v[104:105], v[172:173] op_sel_hi:[1,0]
	v_pk_mul_f32 v[110:111], v[110:111], v[172:173] op_sel_hi:[1,0]
	v_pk_mul_f32 v[108:109], v[108:109], v[172:173] op_sel_hi:[1,0]
	v_pk_mul_f32 v[106:107], v[106:107], v[172:173] op_sel_hi:[1,0]
	v_pk_mul_f32 v[102:103], v[102:103], v[172:173] op_sel_hi:[1,0]
	v_pk_mul_f32 v[100:101], v[100:101], v[172:173] op_sel_hi:[1,0]
	v_pk_mul_f32 v[112:113], v[98:99], v[172:173] op_sel_hi:[1,0]
	v_pk_mul_f32 v[114:115], v[96:97], v[172:173] op_sel_hi:[1,0]
	v_cvt_pk_bf16_f32 v98, v104, v105
	v_cvt_pk_bf16_f32 v96, v108, v109
	v_cvt_pk_bf16_f32 v97, v110, v111
	v_cvt_pk_bf16_f32 v99, v106, v107
	v_cvt_pk_bf16_f32 v100, v100, v101
	v_cvt_pk_bf16_f32 v101, v102, v103
	v_cvt_pk_bf16_f32 v102, v114, v115
	v_cvt_pk_bf16_f32 v103, v112, v113
	v_ashrrev_i32_e32 v179, 31, v178
	s_andn2_b64 s[8:9], exec, s[10:11]
	s_andn2_b64 vcc, exec, s[10:11]
	s_mov_b64 s[10:11], -1
	s_cbranch_vccnz .LBB0_431
	v_mul_lo_u32 v106, s61, v178
	v_mul_lo_u32 v107, s60, v179
	v_mad_u64_u32 v[104:105], s[10:11], s60, v178, 0
	v_add3_u32 v105, v105, v107, v106
	v_lshl_add_u64 v[104:105], v[104:105], 1, v[170:171]
	s_mov_b64 s[10:11], 0
	global_store_dwordx4 v[104:105], v[96:99], off
	global_store_dwordx4 v[104:105], v[100:103], off offset:64

.LBB0_510:
	v_mov_b32_e32 v0, v181
	v_pk_mul_f32 v[2:3], v[0:1], v[116:117] op_sel_hi:[0,1]
	v_pk_mul_f32 v[12:13], v[0:1], v[112:113] op_sel_hi:[0,1]
	v_pk_mul_f32 v[4:5], v[0:1], v[114:115] op_sel_hi:[0,1]
	v_pk_mul_f32 v[6:7], v[0:1], v[118:119] op_sel_hi:[0,1]
	v_pk_mul_f32 v[14:15], v[0:1], v[186:187] op_sel_hi:[0,1]
	v_pk_mul_f32 v[112:113], v[0:1], v[184:185] op_sel_hi:[0,1]
	v_pk_mul_f32 v[114:115], v[0:1], v[188:189] op_sel_hi:[0,1]
	v_pk_mul_f32 v[116:117], v[0:1], v[182:183] op_sel_hi:[0,1]
	v_cvt_pk_bf16_f32 v1, v2, v3
	v_cvt_pk_bf16_f32 v2, v12, v13
	v_cvt_pk_bf16_f32 v0, v4, v5
	v_cvt_pk_bf16_f32 v3, v6, v7
	v_cvt_pk_bf16_f32 v4, v112, v113
	v_cvt_pk_bf16_f32 v5, v14, v15
	v_cvt_pk_bf16_f32 v6, v116, v117
	v_cvt_pk_bf16_f32 v7, v114, v115
	v_ashrrev_i32_e32 v133, 31, v132
	s_andn2_b64 s[8:9], exec, s[48:49]
	s_andn2_b64 vcc, exec, s[48:49]
	s_mov_b64 s[48:49], -1
	s_cbranch_vccnz .LBB0_512
	v_mul_lo_u32 v14, s67, v132
	v_mul_lo_u32 v15, s66, v133
	v_mad_u64_u32 v[12:13], s[48:49], s66, v132, 0
	v_add3_u32 v13, v13, v15, v14
	v_lshl_add_u64 v[12:13], v[12:13], 1, v[8:9]
	s_mov_b64 s[48:49], 0
	global_store_dwordx4 v[12:13], v[0:3], off
	global_store_dwordx4 v[12:13], v[4:7], off offset:64

.LBB0_577:
	s_lshl_b32 s7, s10, 10
	s_sub_i32 s24, s28, s7
	s_ashr_i32 s7, s6, 31
	v_add_u32_e32 v32, s24, v150
	v_lshl_add_u64 v[0:1], s[6:7], 2, v[44:45]
	v_mad_i64_i32 v[2:3], s[6:7], v32, s88, v[0:1]
	s_mul_i32 s6, s10, 0xfe500000
	s_nop 0
	v_add_u32_e32 v4, s6, v62
	v_ashrrev_i32_e32 v5, 31, v4
	v_lshl_add_u64 v[50:51], v[0:1], 0, v[4:5]
	v_add_co_u32_e32 v0, vcc, 0x1b000, v50
	s_nop 0
	s_nop 0
	v_addc_co_u32_e32 v1, vcc, 0, v51, vcc
	global_load_dwordx4 v[24:27], v[2:3], off nt
	global_load_dwordx4 v[28:31], v[0:1], off nt
	v_add_co_u32_e32 v0, vcc, 0x36000, v50
	s_andn2_b64 s[6:7], exec, s[12:13]
	s_nop 0
	v_addc_co_u32_e32 v1, vcc, 0, v51, vcc
	v_add_co_u32_e32 v2, vcc, 0x51000, v50
	s_nop 1
	v_addc_co_u32_e32 v3, vcc, 0, v51, vcc
	global_load_dwordx4 v[16:19], v[0:1], off nt
	global_load_dwordx4 v[20:23], v[2:3], off nt
	v_add_co_u32_e32 v0, vcc, 0x6c000, v50
	s_nop 1
	v_addc_co_u32_e32 v1, vcc, 0, v51, vcc
	v_add_co_u32_e32 v2, vcc, 0x87000, v50
	s_nop 1
	v_addc_co_u32_e32 v3, vcc, 0, v51, vcc
	global_load_dwordx4 v[8:11], v[0:1], off nt
	global_load_dwordx4 v[12:15], v[2:3], off nt
	v_add_co_u32_e32 v0, vcc, 0xa2000, v50
	s_nop 1
	v_addc_co_u32_e32 v1, vcc, 0, v51, vcc
	v_add_co_u32_e32 v4, vcc, 0xbd000, v50
	s_nop 1
	v_addc_co_u32_e32 v5, vcc, 0, v51, vcc
	global_load_dwordx4 v[0:3], v[0:1], off nt
	s_nop 0
	global_load_dwordx4 v[4:7], v[4:5], off nt
	s_andn2_b64 vcc, exec, s[12:13]
	s_cbranch_vccnz .LBB0_600
	v_ashrrev_i32_e32 v33, 31, v32
	s_ashr_i32 s25, s24, 31
	v_lshl_add_u64 v[32:33], v[32:33], 2, s[16:17]
	v_lshl_add_u64 v[34:35], s[24:25], 0, v[150:151]
	global_load_dword v32, v[32:33], off
	v_lshl_add_u64 v[34:35], v[34:35], 2, s[16:17]
	global_load_dword v68, v[34:35], off offset:16
	s_waitcnt vmcnt(1)
	v_pk_mul_f32 v[34:35], v[26:27], v[32:33] op_sel_hi:[1,0]
	v_pk_mul_f32 v[32:33], v[24:25], v[32:33] op_sel_hi:[1,0]
	ds_write2_b32 v52, v32, v33 offset1:1
	ds_write2_b32 v52, v34, v35 offset0:2 offset1:3
	s_waitcnt vmcnt(0)
	v_pk_mul_f32 v[34:35], v[30:31], v[68:69] op_sel_hi:[1,0]
	v_pk_mul_f32 v[32:33], v[28:29], v[68:69] op_sel_hi:[1,0]
	s_cbranch_execnz .LBB0_580

.LBB0_770:
	s_waitcnt lgkmcnt(0)
	s_barrier
	ds_read_b128 v[4:7], v189
	ds_read_b128 v[8:11], v189 offset:32
	s_waitcnt lgkmcnt(1)
	v_mfma_f32_32x32x16_bf16 v[34:49], v[4:7], v[130:133], 0
	ds_read_b128 v[4:7], v189 offset:4608
	ds_read_b128 v[12:15], v189 offset:4640
	s_andn2_b64 vcc, exec, s[26:27]
	s_waitcnt lgkmcnt(1)
	v_mfma_f32_32x32x16_bf16 v[50:65], v[4:7], v[130:133], 0
	v_mfma_f32_32x32x16_bf16 v[34:49], v[8:11], v[134:137], v[34:49]
	ds_read_b128 v[4:7], v189 offset:64
	ds_read_b128 v[8:11], v189 offset:96
	s_waitcnt lgkmcnt(2)
	v_mfma_f32_32x32x16_bf16 v[50:65], v[12:15], v[134:137], v[50:65]
	s_waitcnt lgkmcnt(1)
	v_mfma_f32_32x32x16_bf16 v[34:49], v[4:7], v[138:141], v[34:49]
	ds_read_b128 v[4:7], v189 offset:4672
	ds_read_b128 v[12:15], v189 offset:4704
	s_waitcnt lgkmcnt(1)
	v_mfma_f32_32x32x16_bf16 v[50:65], v[4:7], v[138:141], v[50:65]
	s_andn2_b64 s[4:5], exec, s[26:27]
	v_mfma_f32_32x32x16_bf16 v[34:49], v[8:11], v[142:145], v[34:49]
	s_waitcnt lgkmcnt(0)
	v_mfma_f32_32x32x16_bf16 v[50:65], v[12:15], v[142:145], v[50:65]
	s_cbranch_vccnz .LBB0_772
	s_waitcnt vmcnt(0)
	ds_write_b128 v188, v[150:153] offset:9216

.LBB0_936:
	s_andn2_b64 s[4:5], exec, s[8:9]
	s_andn2_b64 vcc, exec, s[8:9]
	v_readfirstlane_b32 s12, v130
	s_cbranch_vccnz .LBB0_942
	s_ashr_i32 s8, s33, 31
	s_lshr_b32 s8, s8, 29
	s_add_i32 s28, s33, s8
	s_and_b32 s8, s28, -8
	s_sub_i32 s29, s33, s8
	s_cmp_gt_i32 s29, -1
	s_mov_b64 s[8:9], -1
	s_cbranch_scc0 .LBB0_939
	s_lshl_b32 s30, s29, 5
	s_mov_b64 s[8:9], 0

.LBB0_960:
	v_add_co_u32_e32 v132, vcc, 0x2000, v2
	s_nop 0
	s_nop 0
	v_addc_co_u32_e32 v133, vcc, 0, v3, vcc
	global_load_dwordx4 v[152:155], v[132:133], off
	s_andn2_b64 s[8:9], exec, s[6:7]
	s_andn2_b64 vcc, exec, s[6:7]
	s_cbranch_vccnz .LBB0_962
	v_add_co_u32_e32 v132, vcc, 0x12000, v2
	s_nop 1
	v_addc_co_u32_e32 v133, vcc, 0, v3, vcc
	global_load_dwordx4 v[140:143], v[132:133], off

.LBB0_968:
	s_mov_b64 s[48:49], -1
	s_andn2_b64 s[6:7], exec, s[54:55]
	s_andn2_b64 vcc, exec, s[54:55]
	v_cvt_f32_ubyte1_e32 v181, v150
	v_cvt_f32_ubyte3_e32 v179, v150
	v_cvt_f32_ubyte2_e32 v178, v150
	v_cvt_f32_ubyte1_e32 v149, v151
	v_cvt_f32_ubyte3_e32 v137, v151
	v_cvt_f32_ubyte2_e32 v136, v151
	v_cvt_f32_ubyte0_e32 v180, v150
	v_cvt_f32_ubyte0_e32 v148, v151
	s_cbranch_vccnz .LBB0_970
	v_pk_mul_f32 v[150:151], v[180:181], s[26:27] op_sel_hi:[1,0]
	s_lshl_b32 s48, s44, 8
	v_pk_mul_f32 v[150:151], v[96:97], v[150:151]
	s_ashr_i32 s49, s48, 31
	v_cvt_pk_bf16_f32 v182, v150, v151
	v_pk_mul_f32 v[150:151], v[178:179], s[26:27] op_sel_hi:[1,0]
	s_lshl_b32 s12, s62, 1
	v_pk_mul_f32 v[150:151], v[98:99], v[150:151]
	s_nop 0
	v_cvt_pk_bf16_f32 v183, v150, v151
	v_pk_mul_f32 v[150:151], v[148:149], s[26:27] op_sel_hi:[1,0]
	s_nop 0
	v_pk_mul_f32 v[150:151], v[92:93], v[150:151]
	s_nop 0
	v_cvt_pk_bf16_f32 v184, v150, v151
	v_pk_mul_f32 v[150:151], v[136:137], s[26:27] op_sel_hi:[1,0]
	s_nop 0
	v_pk_mul_f32 v[150:151], v[94:95], v[150:151]
	s_nop 0
	v_cvt_pk_bf16_f32 v185, v150, v151
	v_lshl_add_u64 v[150:151], s[48:49], 1, v[176:177]
	v_lshl_add_u64 v[150:151], v[150:151], 0, s[12:13]
	v_lshl_add_u64 v[150:151], v[150:151], 0, v[0:1]
	s_mov_b64 s[48:49], 0
	global_store_dwordx4 v[150:151], v[182:185], off offset:256

.LBB0_1447:
	s_waitcnt lgkmcnt(0)
	s_cmp_lt_i32 s4, 7
	s_cselect_b64 s[0:1], -1, 0
	s_cmp_gt_i32 s5, 6
	s_cselect_b64 s[2:3], -1, 0
	s_and_b64 s[0:1], s[0:1], s[2:3]
	s_andn2_b64 vcc, exec, s[0:1]
	s_cbranch_vccnz .LBB0_1509
	s_load_dword s0, s[92:93], 0x114
	s_load_dwordx2 s[10:11], s[92:93], 0x100
	s_mov_b32 s8, 0x44b00000
	s_mov_b32 s13, 0
	s_mov_b32 s33, 0x3fffe0
	s_waitcnt lgkmcnt(0)
	s_cmp_eq_u32 s0, 12
	s_cselect_b64 s[6:7], -1, 0
	s_cmp_eq_u32 s0, 9
	s_cselect_b64 s[0:1], -1, 0
	s_or_b64 s[0:1], s[6:7], s[0:1]
	s_and_b64 s[0:1], s[0:1], exec
	s_cselect_b32 s0, 2, 1
	s_abs_i32 s3, s46
	v_cvt_f32_u32_e32 v0, s3
	s_sub_i32 s4, 0, s3
	s_ashr_i32 s2, s46, 31
	s_mov_b32 s1, s46
	v_rcp_iflag_f32_e32 v0, v0
	s_mov_b32 s15, s13
	s_mov_b64 s[20:21], 0x80
	s_movk_i32 s66, 0x1600
	v_mul_f32_e32 v0, 0x4f7ffffe, v0
	v_cvt_u32_f32_e32 v0, v0
	v_mov_b32_e32 v207, 1
	v_mov_b64_e32 v[196:197], 0x57f
	s_mov_b32 s67, 0
	v_readfirstlane_b32 s5, v0
	s_mul_i32 s4, s4, s5
	s_mul_hi_u32 s4, s5, s4
	s_add_i32 s5, s5, s4
	s_mul_hi_u32 s4, s5, 0x580
	s_mul_i32 s4, s4, s3
	s_sub_i32 s4, 0x580, s4
	s_sub_i32 s5, s4, s3
	s_cmp_ge_u32 s4, s3
	s_cselect_b32 s4, s5, s4
	s_sub_i32 s5, s4, s3
	s_cmp_ge_u32 s4, s3
	s_cselect_b32 s3, s5, s4
	s_sub_i32 s14, 0x580, s3
	s_lshl_b32 s3, s3, 1
	s_cmp_lg_u32 s3, s46
	s_cselect_b64 s[16:17], -1, 0
	s_cmp_gt_u32 s46, s14
	s_cselect_b64 s[4:5], -1, 0
	s_and_b32 s3, s46, 0xffff
	v_cvt_f32_u32_e32 v1, s3
	s_andn2_b64 s[4:5], exec, s[4:5]
	s_movk_i32 s3, 0xb1
	v_rcp_iflag_f32_e32 v2, v1
	v_mov_b32_e32 v0, 0
	v_mul_f32_e32 v2, 0x44b00000, v2
	v_trunc_f32_e32 v2, v2
	v_cvt_u32_f32_e32 v3, v2
	v_fma_f32 v2, -v2, v1, s8
	v_cmp_ge_f32_e64 s[8:9], |v2|, v1
	s_cmp_lg_u64 s[8:9], 0
	v_readfirstlane_b32 s8, v3
	s_addc_u32 s8, s8, 0
	s_add_i32 s36, 0, 0x23000
	s_xor_b64 s[18:19], s[6:7], -1
	s_and_b32 s37, s8, 0xffff
	s_waitcnt vmcnt(0)
	s_branch .LBB0_1451

.LBB0_1476:
	v_add_u32_e32 v1, 0x10000, v231
	s_waitcnt lgkmcnt(0)
	ds_read_b128 v[180:183], v1
	ds_read_b128 v[184:187], v1 offset:1024
	ds_read_b128 v[188:191], v1 offset:2048
	ds_read_b128 v[192:195], v1 offset:3072
	v_add_u32_e32 v1, 0x14000, v231
	ds_read_b128 v[108:111], v1
	ds_read_b128 v[112:115], v1 offset:1024
	ds_read_b128 v[124:127], v1 offset:2048
	ds_read_b128 v[128:131], v1 offset:3072
	s_andn2_b64 s[8:9], exec, s[58:59]
	s_andn2_b64 vcc, exec, s[58:59]
	s_cbranch_vccnz .LBB0_1478
	ds_read_b128 v[4:7], v233
	ds_read_b128 v[8:11], v233 offset:1024
	ds_read_b128 v[12:15], v233 offset:2048
	ds_read_b128 v[16:19], v233 offset:3072
	ds_read_b128 v[20:23], v233 offset:4096
	ds_read_b128 v[24:27], v233 offset:5120
	ds_read_b128 v[28:31], v233 offset:6144
	ds_read_b128 v[32:35], v233 offset:7168

.LBB0_1480:
	s_barrier
	s_andn2_b64 s[6:7], exec, s[48:49]
	s_andn2_b64 vcc, exec, s[48:49]
	s_cbranch_vccnz .LBB0_1482
	s_waitcnt lgkmcnt(0)
	ds_read_b128 v[4:7], v233 offset:16384
	ds_read_b128 v[8:11], v233 offset:17408
	ds_read_b128 v[12:15], v233 offset:18432
	ds_read_b128 v[16:19], v233 offset:19456
	ds_read_b128 v[20:23], v233 offset:20480
	ds_read_b128 v[24:27], v233 offset:21504
	ds_read_b128 v[28:31], v233 offset:22528
	ds_read_b128 v[32:35], v233 offset:23552

.LBB0_1631:
	s_nop 0
	s_andn2_b64 s[10:11], exec, s[12:13]
	s_andn2_b64 vcc, exec, s[12:13]
	s_mov_b64 s[12:13], s[48:49]
	s_cbranch_vccnz .LBB0_1633
	s_mul_i32 s12, s90, 0x160000
	s_mul_hi_i32 s13, s90, 0x160000
	s_add_u32 s12, s74, s12
	s_addc_u32 s13, s75, s13

.LBB0_1800:
	v_or_b32_e32 v110, s2, v86
	v_ashrrev_i32_e32 v111, 31, v110
	v_lshl_add_u64 v[112:113], v[110:111], 2, s[16:17]
	global_load_dword v114, v[112:113], off
	v_or_b32_e32 v110, s2, v86
	v_or_b32_e32 v112, 4, v110
	v_ashrrev_i32_e32 v113, 31, v112
	v_lshl_add_u64 v[110:111], v[112:113], 2, s[16:17]
	global_load_dword v116, v[110:111], off
	v_or_b32_e32 v110, s2, v86
	v_or_b32_e32 v112, 8, v110
	v_ashrrev_i32_e32 v113, 31, v112
	v_lshl_add_u64 v[110:111], v[112:113], 2, s[16:17]
	global_load_dword v118, v[110:111], off
	v_or_b32_e32 v110, s2, v86
	v_or_b32_e32 v112, 12, v110
	v_ashrrev_i32_e32 v113, 31, v112
	v_lshl_add_u64 v[110:111], v[112:113], 2, s[16:17]
	global_load_dword v120, v[110:111], off
	v_or_b32_e32 v110, s2, v86
	v_or_b32_e32 v112, 16, v110
	v_ashrrev_i32_e32 v113, 31, v112
	v_lshl_add_u64 v[110:111], v[112:113], 2, s[16:17]
	global_load_dword v122, v[110:111], off
	v_or_b32_e32 v110, s2, v86
	v_or_b32_e32 v112, 20, v110
	v_ashrrev_i32_e32 v113, 31, v112
	v_lshl_add_u64 v[110:111], v[112:113], 2, s[16:17]
	global_load_dword v124, v[110:111], off
	v_or_b32_e32 v110, s2, v86
	v_or_b32_e32 v112, 24, v110
	v_ashrrev_i32_e32 v113, 31, v112
	v_lshl_add_u64 v[110:111], v[112:113], 2, s[16:17]
	global_load_dword v126, v[110:111], off
	v_or_b32_e32 v110, s2, v86
	v_or_b32_e32 v112, 28, v110
	v_ashrrev_i32_e32 v113, 31, v112
	v_lshl_add_u64 v[110:111], v[112:113], 2, s[16:17]
	global_load_dword v128, v[110:111], off
	v_or_b32_e32 v110, s2, v86
	v_or_b32_e32 v112, 32, v110
	v_ashrrev_i32_e32 v113, 31, v112
	v_lshl_add_u64 v[112:113], v[112:113], 2, s[16:17]
	global_load_dword v130, v[112:113], off
	v_or_b32_e32 v110, s2, v86
	v_or_b32_e32 v112, 36, v110
	v_ashrrev_i32_e32 v113, 31, v112
	v_lshl_add_u64 v[110:111], v[112:113], 2, s[16:17]
	global_load_dword v132, v[110:111], off
	v_or_b32_e32 v110, s2, v86
	v_or_b32_e32 v112, 40, v110
	v_ashrrev_i32_e32 v113, 31, v112
	v_lshl_add_u64 v[110:111], v[112:113], 2, s[16:17]
	global_load_dword v134, v[110:111], off
	v_or_b32_e32 v110, s2, v86
	v_or_b32_e32 v112, 44, v110
	v_ashrrev_i32_e32 v113, 31, v112
	v_lshl_add_u64 v[110:111], v[112:113], 2, s[16:17]
	global_load_dword v136, v[110:111], off
	v_or_b32_e32 v110, s2, v86
	v_or_b32_e32 v112, 48, v110
	v_ashrrev_i32_e32 v113, 31, v112
	v_lshl_add_u64 v[110:111], v[112:113], 2, s[16:17]
	global_load_dword v138, v[110:111], off
	v_or_b32_e32 v110, s2, v86
	v_or_b32_e32 v112, 52, v110
	v_ashrrev_i32_e32 v113, 31, v112
	v_lshl_add_u64 v[110:111], v[112:113], 2, s[16:17]
	global_load_dword v140, v[110:111], off
	v_or_b32_e32 v110, s2, v86
	v_or_b32_e32 v112, 56, v110
	v_ashrrev_i32_e32 v113, 31, v112
	v_lshl_add_u64 v[110:111], v[112:113], 2, s[16:17]
	global_load_dword v142, v[110:111], off
	v_or_b32_e32 v110, s2, v86
	v_or_b32_e32 v110, 60, v110
	v_ashrrev_i32_e32 v111, 31, v110
	v_lshl_add_u64 v[112:113], v[110:111], 2, s[16:17]
	global_load_dword v144, v[112:113], off
	v_or_b32_e32 v92, s2, v86
	s_andn2_b64 vcc, exec, s[14:15]
	v_mad_i64_i32 v[4:5], s[2:3], v92, s50, v[22:23]
	global_load_dwordx4 v[4:7], v[4:5], off
	v_or_b32_e32 v94, 4, v92
	v_mad_i64_i32 v[24:25], s[2:3], v94, s50, v[22:23]
	global_load_dwordx4 v[24:27], v[24:25], off
	v_or_b32_e32 v96, 8, v92
	v_mad_i64_i32 v[28:29], s[2:3], v96, s50, v[22:23]
	global_load_dwordx4 v[28:31], v[28:29], off
	v_or_b32_e32 v98, 12, v92
	v_mad_i64_i32 v[32:33], s[2:3], v98, s50, v[22:23]
	global_load_dwordx4 v[32:35], v[32:33], off
	v_or_b32_e32 v100, 16, v92
	v_mad_i64_i32 v[38:39], s[2:3], v100, s50, v[22:23]
	global_load_dwordx4 v[38:41], v[38:39], off
	v_or_b32_e32 v102, 20, v92
	v_mad_i64_i32 v[42:43], s[2:3], v102, s50, v[22:23]
	global_load_dwordx4 v[42:45], v[42:43], off
	v_or_b32_e32 v104, 24, v92
	v_mad_i64_i32 v[46:47], s[2:3], v104, s50, v[22:23]
	global_load_dwordx4 v[46:49], v[46:47], off
	v_or_b32_e32 v106, 28, v92
	v_mad_i64_i32 v[88:89], s[2:3], v106, s50, v[22:23]
	global_load_dwordx4 v[88:91], v[88:89], off
	s_mov_b64 s[14:15], 0
	s_and_b64 vcc, exec, vcc
	s_waitcnt vmcnt(7)
	v_mul_f32_e32 v36, v4, v114
	v_mul_f32_e32 v87, v5, v114
	v_mul_f32_e32 v6, v6, v114
	v_mul_f32_e32 v7, v7, v114
	v_or_b32_e32 v94, 40, v92
	s_waitcnt vmcnt(6)
	v_mul_f32_e32 v5, v24, v116
	v_max3_f32 v3, v3, |v36|, |v5|
	v_mul_f32_e32 v5, v25, v116
	v_max3_f32 v2, v2, |v87|, |v5|
	v_mul_f32_e32 v5, v26, v116
	v_max3_f32 v5, v1, |v6|, |v5|
	v_mul_f32_e32 v1, v27, v116
	v_max3_f32 v4, v0, |v7|, |v1|
	v_or_b32_e32 v96, 44, v92
	s_waitcnt vmcnt(5)
	v_mul_f32_e32 v6, v28, v118
	v_mul_f32_e32 v7, v29, v118
	v_mul_f32_e32 v21, v30, v118
	v_mul_f32_e32 v24, v31, v118
	v_or_b32_e32 v98, 48, v92
	v_mad_i64_i32 v[28:29], s[2:3], v96, s50, v[22:23]
	global_load_dwordx4 v[28:31], v[28:29], off
	s_waitcnt vmcnt(5)
	v_mul_f32_e32 v1, v32, v120
	v_max3_f32 v3, v3, |v6|, |v1|
	v_mul_f32_e32 v1, v33, v120
	v_max3_f32 v2, v2, |v7|, |v1|
	v_mul_f32_e32 v1, v34, v120
	v_mul_f32_e32 v0, v35, v120
	v_max3_f32 v5, v5, |v21|, |v1|
	v_max3_f32 v4, v4, |v24|, |v0|
	v_mad_i64_i32 v[32:33], s[2:3], v98, s50, v[22:23]
	global_load_dwordx4 v[32:35], v[32:33], off
	v_or_b32_e32 v100, 52, v92
	s_waitcnt vmcnt(5)
	v_mul_f32_e32 v6, v38, v122
	v_mul_f32_e32 v7, v39, v122
	v_mul_f32_e32 v21, v40, v122
	v_mul_f32_e32 v24, v41, v122
	v_mad_i64_i32 v[38:39], s[2:3], v100, s50, v[22:23]
	global_load_dwordx4 v[38:41], v[38:39], off
	v_or_b32_e32 v102, 56, v92
	s_waitcnt vmcnt(5)
	v_mul_f32_e32 v1, v42, v124
	v_max3_f32 v3, v3, |v6|, |v1|
	v_mul_f32_e32 v1, v43, v124
	v_max3_f32 v2, v2, |v7|, |v1|
	v_mul_f32_e32 v1, v44, v124
	v_mul_f32_e32 v0, v45, v124
	v_max3_f32 v5, v5, |v21|, |v1|
	v_max3_f32 v4, v4, |v24|, |v0|
	v_mad_i64_i32 v[42:43], s[2:3], v102, s50, v[22:23]
	global_load_dwordx4 v[42:45], v[42:43], off
	s_waitcnt vmcnt(5)
	v_mul_f32_e32 v6, v46, v126
	v_mul_f32_e32 v7, v47, v126
	v_mul_f32_e32 v21, v48, v126
	v_mul_f32_e32 v24, v49, v126
	s_waitcnt vmcnt(4)
	v_mul_f32_e32 v1, v88, v128
	v_max3_f32 v36, v3, |v6|, |v1|
	v_mul_f32_e32 v1, v89, v128
	v_or_b32_e32 v88, 32, v92
	v_max3_f32 v87, v2, |v7|, |v1|
	v_mul_f32_e32 v1, v90, v128
	v_mul_f32_e32 v0, v91, v128
	v_max3_f32 v21, v5, |v21|, |v1|
	v_max3_f32 v104, v4, |v24|, |v0|
	v_mad_i64_i32 v[0:1], s[2:3], v88, s50, v[22:23]
	global_load_dwordx4 v[0:3], v[0:1], off
	v_or_b32_e32 v90, 36, v92
	v_mad_i64_i32 v[4:5], s[2:3], v90, s50, v[22:23]
	global_load_dwordx4 v[4:7], v[4:5], off
	v_mad_i64_i32 v[24:25], s[2:3], v94, s50, v[22:23]
	global_load_dwordx4 v[24:27], v[24:25], off
	v_or_b32_e32 v92, 60, v92
	v_mad_i64_i32 v[46:47], s[2:3], v92, s50, v[22:23]
	global_load_dwordx4 v[46:49], v[46:47], off
	s_mov_b32 s2, 64
	s_waitcnt vmcnt(3)
	v_mul_f32_e32 v89, v0, v130
	v_mul_f32_e32 v105, v1, v130
	v_mul_f32_e32 v2, v2, v130
	v_mul_f32_e32 v3, v3, v130
	s_waitcnt vmcnt(2)
	v_mul_f32_e32 v1, v4, v132
	v_max3_f32 v4, v36, |v89|, |v1|
	v_mul_f32_e32 v1, v5, v132
	v_max3_f32 v5, v87, |v105|, |v1|
	v_mul_f32_e32 v1, v6, v132
	v_mul_f32_e32 v0, v7, v132
	v_max3_f32 v2, v21, |v2|, |v1|
	v_max3_f32 v3, v104, |v3|, |v0|
	s_waitcnt vmcnt(1)
	v_mul_f32_e32 v6, v24, v134
	v_mul_f32_e32 v7, v25, v134
	v_mul_f32_e32 v21, v26, v134
	v_mul_f32_e32 v24, v27, v134
	v_mul_f32_e32 v1, v28, v136
	v_max3_f32 v4, v4, |v6|, |v1|
	v_mul_f32_e32 v1, v29, v136
	v_max3_f32 v5, v5, |v7|, |v1|
	v_mul_f32_e32 v1, v30, v136
	v_mul_f32_e32 v0, v31, v136
	v_max3_f32 v2, v2, |v21|, |v1|
	v_max3_f32 v3, v3, |v24|, |v0|
	v_mul_f32_e32 v6, v32, v138
	v_mul_f32_e32 v7, v33, v138
	v_mul_f32_e32 v21, v34, v138
	v_mul_f32_e32 v24, v35, v138
	v_mul_f32_e32 v1, v38, v140
	v_max3_f32 v4, v4, |v6|, |v1|
	v_mul_f32_e32 v1, v39, v140
	v_max3_f32 v5, v5, |v7|, |v1|
	v_mul_f32_e32 v1, v40, v140
	v_mul_f32_e32 v0, v41, v140
	v_max3_f32 v6, v2, |v21|, |v1|
	v_max3_f32 v7, v3, |v24|, |v0|
	v_mul_f32_e32 v2, v42, v142
	v_mul_f32_e32 v21, v43, v142
	v_mul_f32_e32 v24, v44, v142
	v_mul_f32_e32 v25, v45, v142
	s_waitcnt vmcnt(0)
	v_mul_f32_e32 v1, v46, v144
	v_max3_f32 v3, v4, |v2|, |v1|
	v_mul_f32_e32 v1, v47, v144
	v_max3_f32 v2, v5, |v21|, |v1|
	v_mul_f32_e32 v1, v48, v144
	v_mul_f32_e32 v0, v49, v144
	v_max3_f32 v1, v6, |v24|, |v1|
	v_max3_f32 v0, v7, |v25|, |v0|
	s_cbranch_vccz .LBB0_1800
	v_and_b32_e32 v5, 64, v57
	v_xor_b32_e32 v4, 16, v57
	v_add_u32_e32 v5, 64, v5
	v_cmp_lt_i32_e32 vcc, v4, v5
	s_nop 1
	v_cndmask_b32_e32 v4, v57, v4, vcc
	v_lshlrev_b32_e32 v6, 2, v4
	ds_bpermute_b32 v7, v6, v3
	v_xor_b32_e32 v4, 32, v57
	v_cmp_lt_i32_e32 vcc, v4, v5
	ds_bpermute_b32 v5, v6, v2
	ds_bpermute_b32 v24, v6, v0
	v_cndmask_b32_e32 v4, v57, v4, vcc
	v_lshlrev_b32_e32 v21, 2, v4
	s_waitcnt lgkmcnt(2)
	v_max_f32_e32 v4, v7, v7
	ds_bpermute_b32 v7, v6, v1
	v_max_f32_e32 v3, v3, v3
	s_waitcnt lgkmcnt(2)
	v_max_f32_e32 v5, v5, v5
	v_max_f32_e32 v2, v2, v2
	v_max_f32_e32 v1, v1, v1
	s_waitcnt lgkmcnt(0)
	v_max_f32_e32 v6, v7, v7
	v_max_f32_e32 v7, v24, v24
	v_max_f32_e32 v0, v0, v0
	v_max_f32_e32 v3, v3, v4
	v_max_f32_e32 v2, v2, v5
	v_max_f32_e32 v1, v1, v6
	v_max_f32_e32 v0, v0, v7
	ds_bpermute_b32 v4, v21, v3
	ds_bpermute_b32 v5, v21, v2
	ds_bpermute_b32 v6, v21, v1
	ds_bpermute_b32 v7, v21, v0
	s_and_saveexec_b64 s[14:15], s[4:5]
	s_cbranch_execz .LBB0_1803
	s_waitcnt lgkmcnt(0)
	v_max_f32_e32 v7, v7, v7
	v_max_f32_e32 v0, v0, v0
	v_max_f32_e32 v7, v0, v7
	v_max_f32_e32 v0, v6, v6
	v_max_f32_e32 v1, v1, v1
	v_max_f32_e32 v6, v1, v0
	v_max_f32_e32 v0, v5, v5
	v_max_f32_e32 v1, v2, v2
	v_max_f32_e32 v5, v1, v0
	v_max_f32_e32 v0, v4, v4
	v_max_f32_e32 v1, v3, v3
	v_max_f32_e32 v4, v1, v0
	v_add_u32_e32 v0, s90, v52
	ds_write_b128 v0, v[4:7]

.LBB0_1810:
	v_or_b32_e32 v110, s0, v86
	v_ashrrev_i32_e32 v111, 31, v110
	v_lshl_add_u64 v[112:113], v[110:111], 2, s[12:13]
	global_load_dword v114, v[112:113], off
	v_or_b32_e32 v110, s0, v86
	v_or_b32_e32 v112, 4, v110
	v_ashrrev_i32_e32 v113, 31, v112
	v_lshl_add_u64 v[110:111], v[112:113], 2, s[12:13]
	global_load_dword v116, v[110:111], off
	v_or_b32_e32 v110, s0, v86
	v_or_b32_e32 v112, 8, v110
	v_ashrrev_i32_e32 v113, 31, v112
	v_lshl_add_u64 v[110:111], v[112:113], 2, s[12:13]
	global_load_dword v118, v[110:111], off
	v_or_b32_e32 v110, s0, v86
	v_or_b32_e32 v112, 12, v110
	v_ashrrev_i32_e32 v113, 31, v112
	v_lshl_add_u64 v[110:111], v[112:113], 2, s[12:13]
	global_load_dword v120, v[110:111], off
	v_or_b32_e32 v110, s0, v86
	v_or_b32_e32 v112, 16, v110
	v_ashrrev_i32_e32 v113, 31, v112
	v_lshl_add_u64 v[110:111], v[112:113], 2, s[12:13]
	global_load_dword v122, v[110:111], off
	v_or_b32_e32 v110, s0, v86
	v_or_b32_e32 v112, 20, v110
	v_ashrrev_i32_e32 v113, 31, v112
	v_lshl_add_u64 v[110:111], v[112:113], 2, s[12:13]
	global_load_dword v124, v[110:111], off
	v_or_b32_e32 v110, s0, v86
	v_or_b32_e32 v112, 24, v110
	v_ashrrev_i32_e32 v113, 31, v112
	v_lshl_add_u64 v[110:111], v[112:113], 2, s[12:13]
	global_load_dword v126, v[110:111], off
	v_or_b32_e32 v110, s0, v86
	v_or_b32_e32 v112, 28, v110
	v_ashrrev_i32_e32 v113, 31, v112
	v_lshl_add_u64 v[110:111], v[112:113], 2, s[12:13]
	global_load_dword v128, v[110:111], off
	v_or_b32_e32 v110, s0, v86
	v_or_b32_e32 v112, 32, v110
	v_ashrrev_i32_e32 v113, 31, v112
	v_lshl_add_u64 v[112:113], v[112:113], 2, s[12:13]
	global_load_dword v130, v[112:113], off
	v_or_b32_e32 v110, s0, v86
	v_or_b32_e32 v112, 36, v110
	v_ashrrev_i32_e32 v113, 31, v112
	v_lshl_add_u64 v[110:111], v[112:113], 2, s[12:13]
	global_load_dword v132, v[110:111], off
	v_or_b32_e32 v110, s0, v86
	v_or_b32_e32 v112, 40, v110
	v_ashrrev_i32_e32 v113, 31, v112
	v_lshl_add_u64 v[110:111], v[112:113], 2, s[12:13]
	global_load_dword v134, v[110:111], off
	v_or_b32_e32 v110, s0, v86
	v_or_b32_e32 v112, 44, v110
	v_ashrrev_i32_e32 v113, 31, v112
	v_lshl_add_u64 v[110:111], v[112:113], 2, s[12:13]
	global_load_dword v136, v[110:111], off
	v_or_b32_e32 v110, s0, v86
	v_or_b32_e32 v112, 48, v110
	v_ashrrev_i32_e32 v113, 31, v112
	v_lshl_add_u64 v[110:111], v[112:113], 2, s[12:13]
	global_load_dword v138, v[110:111], off
	v_or_b32_e32 v110, s0, v86
	v_or_b32_e32 v112, 52, v110
	v_ashrrev_i32_e32 v113, 31, v112
	v_lshl_add_u64 v[110:111], v[112:113], 2, s[12:13]
	global_load_dword v140, v[110:111], off
	v_or_b32_e32 v110, s0, v86
	v_or_b32_e32 v112, 56, v110
	v_ashrrev_i32_e32 v113, 31, v112
	v_lshl_add_u64 v[110:111], v[112:113], 2, s[12:13]
	global_load_dword v142, v[110:111], off
	v_or_b32_e32 v110, s0, v86
	v_or_b32_e32 v110, 60, v110
	v_ashrrev_i32_e32 v111, 31, v110
	v_lshl_add_u64 v[112:113], v[110:111], 2, s[12:13]
	global_load_dword v144, v[112:113], off
	v_or_b32_e32 v92, s0, v86
	s_andn2_b64 vcc, exec, s[14:15]
	v_mad_i64_i32 v[4:5], s[0:1], v92, s55, v[22:23]
	global_load_dwordx4 v[4:7], v[4:5], off
	v_or_b32_e32 v94, 4, v92
	v_mad_i64_i32 v[24:25], s[0:1], v94, s55, v[22:23]
	global_load_dwordx4 v[24:27], v[24:25], off
	v_or_b32_e32 v96, 8, v92
	v_mad_i64_i32 v[28:29], s[0:1], v96, s55, v[22:23]
	global_load_dwordx4 v[28:31], v[28:29], off
	v_or_b32_e32 v98, 12, v92
	v_mad_i64_i32 v[32:33], s[0:1], v98, s55, v[22:23]
	global_load_dwordx4 v[32:35], v[32:33], off
	v_or_b32_e32 v100, 16, v92
	v_mad_i64_i32 v[38:39], s[0:1], v100, s55, v[22:23]
	global_load_dwordx4 v[38:41], v[38:39], off
	v_or_b32_e32 v102, 20, v92
	v_mad_i64_i32 v[42:43], s[0:1], v102, s55, v[22:23]
	global_load_dwordx4 v[42:45], v[42:43], off
	v_or_b32_e32 v104, 24, v92
	v_mad_i64_i32 v[46:47], s[0:1], v104, s55, v[22:23]
	global_load_dwordx4 v[46:49], v[46:47], off
	v_or_b32_e32 v106, 28, v92
	v_mad_i64_i32 v[88:89], s[0:1], v106, s55, v[22:23]
	global_load_dwordx4 v[88:91], v[88:89], off
	s_mov_b64 s[14:15], 0
	s_and_b64 vcc, exec, vcc
	s_waitcnt vmcnt(7)
	v_mul_f32_e32 v36, v4, v114
	v_mul_f32_e32 v87, v5, v114
	v_mul_f32_e32 v6, v6, v114
	v_mul_f32_e32 v7, v7, v114
	v_or_b32_e32 v94, 40, v92
	s_waitcnt vmcnt(6)
	v_mul_f32_e32 v5, v24, v116
	v_max3_f32 v3, v3, |v36|, |v5|
	v_mul_f32_e32 v5, v25, v116
	v_max3_f32 v2, v2, |v87|, |v5|
	v_mul_f32_e32 v5, v26, v116
	v_max3_f32 v5, v1, |v6|, |v5|
	v_mul_f32_e32 v1, v27, v116
	v_max3_f32 v4, v0, |v7|, |v1|
	v_or_b32_e32 v96, 44, v92
	s_waitcnt vmcnt(5)
	v_mul_f32_e32 v6, v28, v118
	v_mul_f32_e32 v7, v29, v118
	v_mul_f32_e32 v21, v30, v118
	v_mul_f32_e32 v24, v31, v118
	v_or_b32_e32 v98, 48, v92
	v_mad_i64_i32 v[28:29], s[0:1], v96, s55, v[22:23]
	global_load_dwordx4 v[28:31], v[28:29], off
	s_waitcnt vmcnt(5)
	v_mul_f32_e32 v1, v32, v120
	v_max3_f32 v3, v3, |v6|, |v1|
	v_mul_f32_e32 v1, v33, v120
	v_max3_f32 v2, v2, |v7|, |v1|
	v_mul_f32_e32 v1, v34, v120
	v_mul_f32_e32 v0, v35, v120
	v_max3_f32 v5, v5, |v21|, |v1|
	v_max3_f32 v4, v4, |v24|, |v0|
	v_mad_i64_i32 v[32:33], s[0:1], v98, s55, v[22:23]
	global_load_dwordx4 v[32:35], v[32:33], off
	v_or_b32_e32 v100, 52, v92
	s_waitcnt vmcnt(5)
	v_mul_f32_e32 v6, v38, v122
	v_mul_f32_e32 v7, v39, v122
	v_mul_f32_e32 v21, v40, v122
	v_mul_f32_e32 v24, v41, v122
	v_mad_i64_i32 v[38:39], s[0:1], v100, s55, v[22:23]
	global_load_dwordx4 v[38:41], v[38:39], off
	v_or_b32_e32 v102, 56, v92
	s_waitcnt vmcnt(5)
	v_mul_f32_e32 v1, v42, v124
	v_max3_f32 v3, v3, |v6|, |v1|
	v_mul_f32_e32 v1, v43, v124
	v_max3_f32 v2, v2, |v7|, |v1|
	v_mul_f32_e32 v1, v44, v124
	v_mul_f32_e32 v0, v45, v124
	v_max3_f32 v5, v5, |v21|, |v1|
	v_max3_f32 v4, v4, |v24|, |v0|
	v_mad_i64_i32 v[42:43], s[0:1], v102, s55, v[22:23]
	global_load_dwordx4 v[42:45], v[42:43], off
	s_waitcnt vmcnt(5)
	v_mul_f32_e32 v6, v46, v126
	v_mul_f32_e32 v7, v47, v126
	v_mul_f32_e32 v21, v48, v126
	v_mul_f32_e32 v24, v49, v126
	s_waitcnt vmcnt(4)
	v_mul_f32_e32 v1, v88, v128
	v_max3_f32 v36, v3, |v6|, |v1|
	v_mul_f32_e32 v1, v89, v128
	v_or_b32_e32 v88, 32, v92
	v_max3_f32 v87, v2, |v7|, |v1|
	v_mul_f32_e32 v1, v90, v128
	v_mul_f32_e32 v0, v91, v128
	v_max3_f32 v21, v5, |v21|, |v1|
	v_max3_f32 v104, v4, |v24|, |v0|
	v_mad_i64_i32 v[0:1], s[0:1], v88, s55, v[22:23]
	global_load_dwordx4 v[0:3], v[0:1], off
	v_or_b32_e32 v90, 36, v92
	v_mad_i64_i32 v[4:5], s[0:1], v90, s55, v[22:23]
	global_load_dwordx4 v[4:7], v[4:5], off
	v_mad_i64_i32 v[24:25], s[0:1], v94, s55, v[22:23]
	global_load_dwordx4 v[24:27], v[24:25], off
	v_or_b32_e32 v92, 60, v92
	v_mad_i64_i32 v[46:47], s[0:1], v92, s55, v[22:23]
	global_load_dwordx4 v[46:49], v[46:47], off
	s_mov_b32 s0, 64
	s_waitcnt vmcnt(3)
	v_mul_f32_e32 v89, v0, v130
	v_mul_f32_e32 v105, v1, v130
	v_mul_f32_e32 v2, v2, v130
	v_mul_f32_e32 v3, v3, v130
	s_waitcnt vmcnt(2)
	v_mul_f32_e32 v1, v4, v132
	v_max3_f32 v4, v36, |v89|, |v1|
	v_mul_f32_e32 v1, v5, v132
	v_max3_f32 v5, v87, |v105|, |v1|
	v_mul_f32_e32 v1, v6, v132
	v_mul_f32_e32 v0, v7, v132
	v_max3_f32 v2, v21, |v2|, |v1|
	v_max3_f32 v3, v104, |v3|, |v0|
	s_waitcnt vmcnt(1)
	v_mul_f32_e32 v6, v24, v134
	v_mul_f32_e32 v7, v25, v134
	v_mul_f32_e32 v21, v26, v134
	v_mul_f32_e32 v24, v27, v134
	v_mul_f32_e32 v1, v28, v136
	v_max3_f32 v4, v4, |v6|, |v1|
	v_mul_f32_e32 v1, v29, v136
	v_max3_f32 v5, v5, |v7|, |v1|
	v_mul_f32_e32 v1, v30, v136
	v_mul_f32_e32 v0, v31, v136
	v_max3_f32 v2, v2, |v21|, |v1|
	v_max3_f32 v3, v3, |v24|, |v0|
	v_mul_f32_e32 v6, v32, v138
	v_mul_f32_e32 v7, v33, v138
	v_mul_f32_e32 v21, v34, v138
	v_mul_f32_e32 v24, v35, v138
	v_mul_f32_e32 v1, v38, v140
	v_max3_f32 v4, v4, |v6|, |v1|
	v_mul_f32_e32 v1, v39, v140
	v_max3_f32 v5, v5, |v7|, |v1|
	v_mul_f32_e32 v1, v40, v140
	v_mul_f32_e32 v0, v41, v140
	v_max3_f32 v6, v2, |v21|, |v1|
	v_max3_f32 v7, v3, |v24|, |v0|
	v_mul_f32_e32 v2, v42, v142
	v_mul_f32_e32 v21, v43, v142
	v_mul_f32_e32 v24, v44, v142
	v_mul_f32_e32 v25, v45, v142
	s_waitcnt vmcnt(0)
	v_mul_f32_e32 v1, v46, v144
	v_max3_f32 v3, v4, |v2|, |v1|
	v_mul_f32_e32 v1, v47, v144
	v_max3_f32 v2, v5, |v21|, |v1|
	v_mul_f32_e32 v1, v48, v144
	v_mul_f32_e32 v0, v49, v144
	v_max3_f32 v1, v6, |v24|, |v1|
	v_max3_f32 v0, v7, |v25|, |v0|
	s_cbranch_vccz .LBB0_1810
	v_and_b32_e32 v5, 64, v57
	v_xor_b32_e32 v4, 16, v57
	v_add_u32_e32 v5, 64, v5
	v_cmp_lt_i32_e32 vcc, v4, v5
	s_nop 1
	v_cndmask_b32_e32 v4, v57, v4, vcc
	v_lshlrev_b32_e32 v6, 2, v4
	ds_bpermute_b32 v7, v6, v3
	v_xor_b32_e32 v4, 32, v57
	v_cmp_lt_i32_e32 vcc, v4, v5
	ds_bpermute_b32 v5, v6, v2
	ds_bpermute_b32 v24, v6, v0
	v_cndmask_b32_e32 v4, v57, v4, vcc
	v_lshlrev_b32_e32 v21, 2, v4
	s_waitcnt lgkmcnt(2)
	v_max_f32_e32 v4, v7, v7
	ds_bpermute_b32 v7, v6, v1
	v_max_f32_e32 v3, v3, v3
	s_waitcnt lgkmcnt(2)
	v_max_f32_e32 v5, v5, v5
	v_max_f32_e32 v2, v2, v2
	v_max_f32_e32 v1, v1, v1
	s_waitcnt lgkmcnt(0)
	v_max_f32_e32 v6, v7, v7
	v_max_f32_e32 v7, v24, v24
	v_max_f32_e32 v0, v0, v0
	v_max_f32_e32 v3, v3, v4
	v_max_f32_e32 v2, v2, v5
	v_max_f32_e32 v1, v1, v6
	v_max_f32_e32 v0, v0, v7
	ds_bpermute_b32 v4, v21, v3
	ds_bpermute_b32 v5, v21, v2
	ds_bpermute_b32 v6, v21, v1
	ds_bpermute_b32 v7, v21, v0
	s_and_saveexec_b64 s[14:15], s[4:5]
	s_cbranch_execz .LBB0_1813
	s_waitcnt lgkmcnt(0)
	v_max_f32_e32 v7, v7, v7
	v_max_f32_e32 v0, v0, v0
	v_max_f32_e32 v7, v0, v7
	v_max_f32_e32 v0, v6, v6
	v_max_f32_e32 v1, v1, v1
	v_max_f32_e32 v6, v1, v0
	v_max_f32_e32 v0, v5, v5
	v_max_f32_e32 v1, v2, v2
	v_max_f32_e32 v5, v1, v0
	v_max_f32_e32 v0, v4, v4
	v_max_f32_e32 v1, v3, v3
	v_max_f32_e32 v4, v1, v0
	v_add_u32_e32 v0, s90, v52
	ds_write_b128 v0, v[4:7]

.LBB0_1834:
	v_or_b32_e32 v110, s1, v86
	v_ashrrev_i32_e32 v111, 31, v110
	v_lshl_add_u64 v[112:113], v[110:111], 2, s[12:13]
	global_load_dword v114, v[112:113], off
	v_or_b32_e32 v110, s1, v86
	v_or_b32_e32 v112, 4, v110
	v_ashrrev_i32_e32 v113, 31, v112
	v_lshl_add_u64 v[110:111], v[112:113], 2, s[12:13]
	global_load_dword v116, v[110:111], off
	v_or_b32_e32 v110, s1, v86
	v_or_b32_e32 v112, 8, v110
	v_ashrrev_i32_e32 v113, 31, v112
	v_lshl_add_u64 v[110:111], v[112:113], 2, s[12:13]
	global_load_dword v118, v[110:111], off
	v_or_b32_e32 v110, s1, v86
	v_or_b32_e32 v112, 12, v110
	v_ashrrev_i32_e32 v113, 31, v112
	v_lshl_add_u64 v[110:111], v[112:113], 2, s[12:13]
	global_load_dword v120, v[110:111], off
	v_or_b32_e32 v110, s1, v86
	v_or_b32_e32 v112, 16, v110
	v_ashrrev_i32_e32 v113, 31, v112
	v_lshl_add_u64 v[110:111], v[112:113], 2, s[12:13]
	global_load_dword v122, v[110:111], off
	v_or_b32_e32 v110, s1, v86
	v_or_b32_e32 v112, 20, v110
	v_ashrrev_i32_e32 v113, 31, v112
	v_lshl_add_u64 v[110:111], v[112:113], 2, s[12:13]
	global_load_dword v124, v[110:111], off
	v_or_b32_e32 v110, s1, v86
	v_or_b32_e32 v112, 24, v110
	v_ashrrev_i32_e32 v113, 31, v112
	v_lshl_add_u64 v[110:111], v[112:113], 2, s[12:13]
	global_load_dword v126, v[110:111], off
	v_or_b32_e32 v110, s1, v86
	v_or_b32_e32 v112, 28, v110
	v_ashrrev_i32_e32 v113, 31, v112
	v_lshl_add_u64 v[110:111], v[112:113], 2, s[12:13]
	global_load_dword v128, v[110:111], off
	v_or_b32_e32 v110, s1, v86
	v_or_b32_e32 v112, 32, v110
	v_ashrrev_i32_e32 v113, 31, v112
	v_lshl_add_u64 v[112:113], v[112:113], 2, s[12:13]
	global_load_dword v130, v[112:113], off
	v_or_b32_e32 v110, s1, v86
	v_or_b32_e32 v112, 36, v110
	v_ashrrev_i32_e32 v113, 31, v112
	v_lshl_add_u64 v[110:111], v[112:113], 2, s[12:13]
	global_load_dword v132, v[110:111], off
	v_or_b32_e32 v110, s1, v86
	v_or_b32_e32 v112, 40, v110
	v_ashrrev_i32_e32 v113, 31, v112
	v_lshl_add_u64 v[110:111], v[112:113], 2, s[12:13]
	global_load_dword v134, v[110:111], off
	v_or_b32_e32 v110, s1, v86
	v_or_b32_e32 v112, 44, v110
	v_ashrrev_i32_e32 v113, 31, v112
	v_lshl_add_u64 v[110:111], v[112:113], 2, s[12:13]
	global_load_dword v136, v[110:111], off
	v_or_b32_e32 v110, s1, v86
	v_or_b32_e32 v112, 48, v110
	v_ashrrev_i32_e32 v113, 31, v112
	v_lshl_add_u64 v[110:111], v[112:113], 2, s[12:13]
	global_load_dword v138, v[110:111], off
	v_or_b32_e32 v110, s1, v86
	v_or_b32_e32 v112, 52, v110
	v_ashrrev_i32_e32 v113, 31, v112
	v_lshl_add_u64 v[110:111], v[112:113], 2, s[12:13]
	global_load_dword v140, v[110:111], off
	v_or_b32_e32 v110, s1, v86
	v_or_b32_e32 v112, 56, v110
	v_ashrrev_i32_e32 v113, 31, v112
	v_lshl_add_u64 v[110:111], v[112:113], 2, s[12:13]
	global_load_dword v142, v[110:111], off
	v_or_b32_e32 v110, s1, v86
	v_or_b32_e32 v110, 60, v110
	v_ashrrev_i32_e32 v111, 31, v110
	v_lshl_add_u64 v[112:113], v[110:111], 2, s[12:13]
	global_load_dword v144, v[112:113], off
	v_or_b32_e32 v92, s1, v86
	s_andn2_b64 vcc, exec, s[14:15]
	v_mad_i64_i32 v[4:5], s[2:3], v92, s55, v[22:23]
	global_load_dwordx4 v[4:7], v[4:5], off
	v_or_b32_e32 v94, 4, v92
	v_mad_i64_i32 v[24:25], s[2:3], v94, s55, v[22:23]
	global_load_dwordx4 v[24:27], v[24:25], off
	v_or_b32_e32 v96, 8, v92
	v_mad_i64_i32 v[28:29], s[2:3], v96, s55, v[22:23]
	global_load_dwordx4 v[28:31], v[28:29], off
	v_or_b32_e32 v98, 12, v92
	v_mad_i64_i32 v[32:33], s[2:3], v98, s55, v[22:23]
	global_load_dwordx4 v[32:35], v[32:33], off
	v_or_b32_e32 v100, 16, v92
	v_mad_i64_i32 v[38:39], s[2:3], v100, s55, v[22:23]
	global_load_dwordx4 v[38:41], v[38:39], off
	v_or_b32_e32 v102, 20, v92
	v_mad_i64_i32 v[42:43], s[2:3], v102, s55, v[22:23]
	global_load_dwordx4 v[42:45], v[42:43], off
	v_or_b32_e32 v104, 24, v92
	v_mad_i64_i32 v[46:47], s[2:3], v104, s55, v[22:23]
	global_load_dwordx4 v[46:49], v[46:47], off
	v_or_b32_e32 v106, 28, v92
	v_mad_i64_i32 v[88:89], s[2:3], v106, s55, v[22:23]
	global_load_dwordx4 v[88:91], v[88:89], off
	s_mov_b32 s1, 64
	s_mov_b64 s[14:15], 0
	s_and_b64 vcc, exec, vcc
	s_waitcnt vmcnt(7)
	v_mul_f32_e32 v36, v4, v114
	v_mul_f32_e32 v87, v5, v114
	v_mul_f32_e32 v6, v6, v114
	v_mul_f32_e32 v7, v7, v114
	v_or_b32_e32 v94, 40, v92
	s_waitcnt vmcnt(6)
	v_mul_f32_e32 v5, v24, v116
	v_max3_f32 v3, v3, |v36|, |v5|
	v_mul_f32_e32 v5, v25, v116
	v_max3_f32 v2, v2, |v87|, |v5|
	v_mul_f32_e32 v5, v26, v116
	v_max3_f32 v5, v1, |v6|, |v5|
	v_mul_f32_e32 v1, v27, v116
	v_max3_f32 v4, v0, |v7|, |v1|
	v_or_b32_e32 v96, 44, v92
	s_waitcnt vmcnt(5)
	v_mul_f32_e32 v6, v28, v118
	v_mul_f32_e32 v7, v29, v118
	v_mul_f32_e32 v21, v30, v118
	v_mul_f32_e32 v24, v31, v118
	v_or_b32_e32 v98, 48, v92
	v_mad_i64_i32 v[28:29], s[2:3], v96, s55, v[22:23]
	global_load_dwordx4 v[28:31], v[28:29], off
	s_waitcnt vmcnt(5)
	v_mul_f32_e32 v1, v32, v120
	v_max3_f32 v3, v3, |v6|, |v1|
	v_mul_f32_e32 v1, v33, v120
	v_max3_f32 v2, v2, |v7|, |v1|
	v_mul_f32_e32 v1, v34, v120
	v_mul_f32_e32 v0, v35, v120
	v_max3_f32 v5, v5, |v21|, |v1|
	v_max3_f32 v4, v4, |v24|, |v0|
	v_mad_i64_i32 v[32:33], s[2:3], v98, s55, v[22:23]
	global_load_dwordx4 v[32:35], v[32:33], off
	v_or_b32_e32 v100, 52, v92
	s_waitcnt vmcnt(5)
	v_mul_f32_e32 v6, v38, v122
	v_mul_f32_e32 v7, v39, v122
	v_mul_f32_e32 v21, v40, v122
	v_mul_f32_e32 v24, v41, v122
	v_mad_i64_i32 v[38:39], s[2:3], v100, s55, v[22:23]
	global_load_dwordx4 v[38:41], v[38:39], off
	v_or_b32_e32 v102, 56, v92
	s_waitcnt vmcnt(5)
	v_mul_f32_e32 v1, v42, v124
	v_max3_f32 v3, v3, |v6|, |v1|
	v_mul_f32_e32 v1, v43, v124
	v_max3_f32 v2, v2, |v7|, |v1|
	v_mul_f32_e32 v1, v44, v124
	v_mul_f32_e32 v0, v45, v124
	v_max3_f32 v5, v5, |v21|, |v1|
	v_max3_f32 v4, v4, |v24|, |v0|
	v_mad_i64_i32 v[42:43], s[2:3], v102, s55, v[22:23]
	global_load_dwordx4 v[42:45], v[42:43], off
	s_waitcnt vmcnt(5)
	v_mul_f32_e32 v6, v46, v126
	v_mul_f32_e32 v7, v47, v126
	v_mul_f32_e32 v21, v48, v126
	v_mul_f32_e32 v24, v49, v126
	s_waitcnt vmcnt(4)
	v_mul_f32_e32 v1, v88, v128
	v_max3_f32 v36, v3, |v6|, |v1|
	v_mul_f32_e32 v1, v89, v128
	v_or_b32_e32 v88, 32, v92
	v_max3_f32 v87, v2, |v7|, |v1|
	v_mul_f32_e32 v1, v90, v128
	v_mul_f32_e32 v0, v91, v128
	v_max3_f32 v21, v5, |v21|, |v1|
	v_max3_f32 v104, v4, |v24|, |v0|
	v_mad_i64_i32 v[0:1], s[2:3], v88, s55, v[22:23]
	global_load_dwordx4 v[0:3], v[0:1], off
	v_or_b32_e32 v90, 36, v92
	v_mad_i64_i32 v[4:5], s[2:3], v90, s55, v[22:23]
	global_load_dwordx4 v[4:7], v[4:5], off
	v_mad_i64_i32 v[24:25], s[2:3], v94, s55, v[22:23]
	global_load_dwordx4 v[24:27], v[24:25], off
	v_or_b32_e32 v92, 60, v92
	v_mad_i64_i32 v[46:47], s[2:3], v92, s55, v[22:23]
	global_load_dwordx4 v[46:49], v[46:47], off
	s_waitcnt vmcnt(3)
	v_mul_f32_e32 v89, v0, v130
	v_mul_f32_e32 v105, v1, v130
	v_mul_f32_e32 v2, v2, v130
	v_mul_f32_e32 v3, v3, v130
	s_waitcnt vmcnt(2)
	v_mul_f32_e32 v1, v4, v132
	v_max3_f32 v4, v36, |v89|, |v1|
	v_mul_f32_e32 v1, v5, v132
	v_max3_f32 v5, v87, |v105|, |v1|
	v_mul_f32_e32 v1, v6, v132
	v_mul_f32_e32 v0, v7, v132
	v_max3_f32 v2, v21, |v2|, |v1|
	v_max3_f32 v3, v104, |v3|, |v0|
	s_waitcnt vmcnt(1)
	v_mul_f32_e32 v6, v24, v134
	v_mul_f32_e32 v7, v25, v134
	v_mul_f32_e32 v21, v26, v134
	v_mul_f32_e32 v24, v27, v134
	v_mul_f32_e32 v1, v28, v136
	v_max3_f32 v4, v4, |v6|, |v1|
	v_mul_f32_e32 v1, v29, v136
	v_max3_f32 v5, v5, |v7|, |v1|
	v_mul_f32_e32 v1, v30, v136
	v_mul_f32_e32 v0, v31, v136
	v_max3_f32 v2, v2, |v21|, |v1|
	v_max3_f32 v3, v3, |v24|, |v0|
	v_mul_f32_e32 v6, v32, v138
	v_mul_f32_e32 v7, v33, v138
	v_mul_f32_e32 v21, v34, v138
	v_mul_f32_e32 v24, v35, v138
	v_mul_f32_e32 v1, v38, v140
	v_max3_f32 v4, v4, |v6|, |v1|
	v_mul_f32_e32 v1, v39, v140
	v_max3_f32 v5, v5, |v7|, |v1|
	v_mul_f32_e32 v1, v40, v140
	v_mul_f32_e32 v0, v41, v140
	v_max3_f32 v6, v2, |v21|, |v1|
	v_max3_f32 v7, v3, |v24|, |v0|
	v_mul_f32_e32 v2, v42, v142
	v_mul_f32_e32 v21, v43, v142
	v_mul_f32_e32 v24, v44, v142
	v_mul_f32_e32 v25, v45, v142
	s_waitcnt vmcnt(0)
	v_mul_f32_e32 v1, v46, v144
	v_max3_f32 v3, v4, |v2|, |v1|
	v_mul_f32_e32 v1, v47, v144
	v_max3_f32 v2, v5, |v21|, |v1|
	v_mul_f32_e32 v1, v48, v144
	v_mul_f32_e32 v0, v49, v144
	v_max3_f32 v1, v6, |v24|, |v1|
	v_max3_f32 v0, v7, |v25|, |v0|
	s_cbranch_vccz .LBB0_1834
	v_and_b32_e32 v5, 64, v57
	v_xor_b32_e32 v4, 16, v57
	v_add_u32_e32 v5, 64, v5
	v_cmp_lt_i32_e32 vcc, v4, v5
	s_nop 1
	v_cndmask_b32_e32 v4, v57, v4, vcc
	v_lshlrev_b32_e32 v6, 2, v4
	ds_bpermute_b32 v7, v6, v3
	v_xor_b32_e32 v4, 32, v57
	v_cmp_lt_i32_e32 vcc, v4, v5
	ds_bpermute_b32 v5, v6, v2
	ds_bpermute_b32 v24, v6, v0
	v_cndmask_b32_e32 v4, v57, v4, vcc
	v_lshlrev_b32_e32 v21, 2, v4
	s_waitcnt lgkmcnt(2)
	v_max_f32_e32 v4, v7, v7
	ds_bpermute_b32 v7, v6, v1
	v_max_f32_e32 v3, v3, v3
	s_waitcnt lgkmcnt(2)
	v_max_f32_e32 v5, v5, v5
	v_max_f32_e32 v2, v2, v2
	v_max_f32_e32 v1, v1, v1
	s_waitcnt lgkmcnt(0)
	v_max_f32_e32 v6, v7, v7
	v_max_f32_e32 v7, v24, v24
	v_max_f32_e32 v0, v0, v0
	v_max_f32_e32 v3, v3, v4
	v_max_f32_e32 v2, v2, v5
	v_max_f32_e32 v1, v1, v6
	v_max_f32_e32 v0, v0, v7
	ds_bpermute_b32 v4, v21, v3
	ds_bpermute_b32 v5, v21, v2
	ds_bpermute_b32 v6, v21, v1
	ds_bpermute_b32 v7, v21, v0
	s_and_saveexec_b64 s[14:15], s[4:5]
	s_cbranch_execz .LBB0_1837
	s_waitcnt lgkmcnt(0)
	v_max_f32_e32 v7, v7, v7
	v_max_f32_e32 v0, v0, v0
	v_max_f32_e32 v7, v0, v7
	v_max_f32_e32 v0, v6, v6
	v_max_f32_e32 v1, v1, v1
	v_max_f32_e32 v6, v1, v0
	v_max_f32_e32 v0, v5, v5
	v_max_f32_e32 v1, v2, v2
	v_max_f32_e32 v5, v1, v0
	v_max_f32_e32 v0, v4, v4
	v_max_f32_e32 v1, v3, v3
	v_max_f32_e32 v4, v1, v0
	v_add_u32_e32 v0, s90, v52
	ds_write_b128 v0, v[4:7]

.LBB0_1871:
	s_lshl_b32 s36, s26, 10
	s_sub_i32 s5, s3, s36
	v_add_u32_e32 v52, s5, v62
	s_ashr_i32 s5, s4, 31
	v_lshl_add_u64 v[0:1], s[4:5], 2, v[46:47]
	v_mad_i64_i32 v[2:3], s[4:5], v52, s55, v[0:1]
	s_mul_i32 s4, s26, 0xfe500000
	s_nop 0
	v_add_u32_e32 v4, s4, v73
	v_ashrrev_i32_e32 v5, 31, v4
	v_lshl_add_u64 v[54:55], v[0:1], 0, v[4:5]
	v_add_co_u32_e32 v0, vcc, s80, v54
	s_nop 0
	s_nop 0
	v_addc_co_u32_e32 v1, vcc, 0, v55, vcc
	global_load_dwordx4 v[24:27], v[2:3], off nt
	global_load_dwordx4 v[28:31], v[0:1], off nt
	v_add_co_u32_e32 v0, vcc, s81, v54
	s_andn2_b64 s[4:5], exec, s[20:21]
	s_nop 0
	v_addc_co_u32_e32 v1, vcc, 0, v55, vcc
	v_add_co_u32_e32 v2, vcc, s82, v54
	v_ashrrev_i32_e32 v53, 31, v52
	s_nop 0
	v_addc_co_u32_e32 v3, vcc, 0, v55, vcc
	global_load_dwordx4 v[16:19], v[0:1], off nt
	global_load_dwordx4 v[20:23], v[2:3], off nt
	v_add_co_u32_e32 v0, vcc, s83, v54
	s_nop 1
	v_addc_co_u32_e32 v1, vcc, 0, v55, vcc
	v_add_co_u32_e32 v2, vcc, 0x87000, v54
	s_nop 1
	v_addc_co_u32_e32 v3, vcc, 0, v55, vcc
	global_load_dwordx4 v[8:11], v[0:1], off nt
	global_load_dwordx4 v[12:15], v[2:3], off nt
	v_add_co_u32_e32 v0, vcc, 0xa2000, v54
	s_nop 1
	v_addc_co_u32_e32 v1, vcc, 0, v55, vcc
	v_add_co_u32_e32 v4, vcc, 0xbd000, v54
	s_nop 1
	v_addc_co_u32_e32 v5, vcc, 0, v55, vcc
	global_load_dwordx4 v[0:3], v[0:1], off nt
	s_nop 0
	global_load_dwordx4 v[4:7], v[4:5], off nt
	s_andn2_b64 vcc, exec, s[20:21]
	s_cbranch_vccnz .LBB0_1894
	v_add_u32_e32 v34, 4, v52
	v_lshl_add_u64 v[32:33], v[52:53], 2, s[12:13]
	v_ashrrev_i32_e32 v35, 31, v34
	global_load_dword v32, v[32:33], off
	v_lshl_add_u64 v[34:35], v[34:35], 2, s[12:13]
	global_load_dword v78, v[34:35], off
	s_waitcnt vmcnt(1)
	v_pk_mul_f32 v[34:35], v[26:27], v[32:33] op_sel_hi:[1,0]
	v_pk_mul_f32 v[32:33], v[24:25], v[32:33] op_sel_hi:[1,0]
	ds_write2_b32 v71, v32, v33 offset1:1
	ds_write2_b32 v71, v34, v35 offset0:2 offset1:3
	s_waitcnt vmcnt(0)
	v_pk_mul_f32 v[34:35], v[30:31], v[78:79] op_sel_hi:[1,0]
	v_pk_mul_f32 v[32:33], v[28:29], v[78:79] op_sel_hi:[1,0]
	s_cbranch_execnz .LBB0_1874

.LBB0_1911:
	v_or_b32_e32 v108, s2, v85
	v_ashrrev_i32_e32 v109, 31, v108
	v_lshl_add_u64 v[110:111], v[108:109], 2, s[16:17]
	global_load_dword v112, v[110:111], off
	v_or_b32_e32 v108, s2, v85
	v_or_b32_e32 v110, 4, v108
	v_ashrrev_i32_e32 v111, 31, v110
	v_lshl_add_u64 v[108:109], v[110:111], 2, s[16:17]
	global_load_dword v114, v[108:109], off
	v_or_b32_e32 v108, s2, v85
	v_or_b32_e32 v110, 8, v108
	v_ashrrev_i32_e32 v111, 31, v110
	v_lshl_add_u64 v[108:109], v[110:111], 2, s[16:17]
	global_load_dword v116, v[108:109], off
	v_or_b32_e32 v108, s2, v85
	v_or_b32_e32 v110, 12, v108
	v_ashrrev_i32_e32 v111, 31, v110
	v_lshl_add_u64 v[108:109], v[110:111], 2, s[16:17]
	global_load_dword v118, v[108:109], off
	v_or_b32_e32 v108, s2, v85
	v_or_b32_e32 v110, 16, v108
	v_ashrrev_i32_e32 v111, 31, v110
	v_lshl_add_u64 v[108:109], v[110:111], 2, s[16:17]
	global_load_dword v120, v[108:109], off
	v_or_b32_e32 v108, s2, v85
	v_or_b32_e32 v110, 20, v108
	v_ashrrev_i32_e32 v111, 31, v110
	v_lshl_add_u64 v[108:109], v[110:111], 2, s[16:17]
	global_load_dword v122, v[108:109], off
	v_or_b32_e32 v108, s2, v85
	v_or_b32_e32 v110, 24, v108
	v_ashrrev_i32_e32 v111, 31, v110
	v_lshl_add_u64 v[108:109], v[110:111], 2, s[16:17]
	global_load_dword v124, v[108:109], off
	v_or_b32_e32 v108, s2, v85
	v_or_b32_e32 v110, 28, v108
	v_ashrrev_i32_e32 v111, 31, v110
	v_lshl_add_u64 v[108:109], v[110:111], 2, s[16:17]
	global_load_dword v126, v[108:109], off
	v_or_b32_e32 v108, s2, v85
	v_or_b32_e32 v110, 32, v108
	v_ashrrev_i32_e32 v111, 31, v110
	v_lshl_add_u64 v[110:111], v[110:111], 2, s[16:17]
	global_load_dword v128, v[110:111], off
	v_or_b32_e32 v108, s2, v85
	v_or_b32_e32 v110, 36, v108
	v_ashrrev_i32_e32 v111, 31, v110
	v_lshl_add_u64 v[108:109], v[110:111], 2, s[16:17]
	global_load_dword v130, v[108:109], off
	v_or_b32_e32 v108, s2, v85
	v_or_b32_e32 v110, 40, v108
	v_ashrrev_i32_e32 v111, 31, v110
	v_lshl_add_u64 v[108:109], v[110:111], 2, s[16:17]
	global_load_dword v132, v[108:109], off
	v_or_b32_e32 v108, s2, v85
	v_or_b32_e32 v110, 44, v108
	v_ashrrev_i32_e32 v111, 31, v110
	v_lshl_add_u64 v[108:109], v[110:111], 2, s[16:17]
	global_load_dword v134, v[108:109], off
	v_or_b32_e32 v108, s2, v85
	v_or_b32_e32 v110, 48, v108
	v_ashrrev_i32_e32 v111, 31, v110
	v_lshl_add_u64 v[108:109], v[110:111], 2, s[16:17]
	global_load_dword v136, v[108:109], off
	v_or_b32_e32 v108, s2, v85
	v_or_b32_e32 v110, 52, v108
	v_ashrrev_i32_e32 v111, 31, v110
	v_lshl_add_u64 v[108:109], v[110:111], 2, s[16:17]
	global_load_dword v138, v[108:109], off
	v_or_b32_e32 v108, s2, v85
	v_or_b32_e32 v110, 56, v108
	v_ashrrev_i32_e32 v111, 31, v110
	v_lshl_add_u64 v[108:109], v[110:111], 2, s[16:17]
	global_load_dword v140, v[108:109], off
	v_or_b32_e32 v108, s2, v85
	v_or_b32_e32 v108, 60, v108
	v_ashrrev_i32_e32 v109, 31, v108
	v_lshl_add_u64 v[110:111], v[108:109], 2, s[16:17]
	global_load_dword v142, v[110:111], off
	v_or_b32_e32 v90, s2, v85
	s_andn2_b64 vcc, exec, s[14:15]
	v_mad_i64_i32 v[4:5], s[2:3], v90, s48, v[22:23]
	global_load_dwordx4 v[4:7], v[4:5], off
	v_or_b32_e32 v92, 4, v90
	v_mad_i64_i32 v[24:25], s[2:3], v92, s48, v[22:23]
	global_load_dwordx4 v[24:27], v[24:25], off
	v_or_b32_e32 v94, 8, v90
	v_mad_i64_i32 v[28:29], s[2:3], v94, s48, v[22:23]
	global_load_dwordx4 v[28:31], v[28:29], off
	v_or_b32_e32 v96, 12, v90
	v_mad_i64_i32 v[32:33], s[2:3], v96, s48, v[22:23]
	global_load_dwordx4 v[32:35], v[32:33], off
	v_or_b32_e32 v98, 16, v90
	v_mad_i64_i32 v[38:39], s[2:3], v98, s48, v[22:23]
	global_load_dwordx4 v[38:41], v[38:39], off
	v_or_b32_e32 v100, 20, v90
	v_mad_i64_i32 v[42:43], s[2:3], v100, s48, v[22:23]
	global_load_dwordx4 v[42:45], v[42:43], off
	v_or_b32_e32 v102, 24, v90
	v_mad_i64_i32 v[46:47], s[2:3], v102, s48, v[22:23]
	global_load_dwordx4 v[46:49], v[46:47], off
	v_or_b32_e32 v104, 28, v90
	v_mad_i64_i32 v[86:87], s[2:3], v104, s48, v[22:23]
	global_load_dwordx4 v[86:89], v[86:87], off
	s_mov_b64 s[14:15], 0
	s_and_b64 vcc, exec, vcc
	s_waitcnt vmcnt(7)
	v_mul_f32_e32 v36, v4, v112
	v_mul_f32_e32 v91, v5, v112
	v_mul_f32_e32 v6, v6, v112
	v_mul_f32_e32 v7, v7, v112
	v_or_b32_e32 v92, 40, v90
	s_waitcnt vmcnt(6)
	v_mul_f32_e32 v5, v24, v114
	v_max3_f32 v3, v3, |v36|, |v5|
	v_mul_f32_e32 v5, v25, v114
	v_max3_f32 v2, v2, |v91|, |v5|
	v_mul_f32_e32 v5, v26, v114
	v_max3_f32 v5, v1, |v6|, |v5|
	v_mul_f32_e32 v1, v27, v114
	v_max3_f32 v4, v0, |v7|, |v1|
	v_or_b32_e32 v94, 44, v90
	s_waitcnt vmcnt(5)
	v_mul_f32_e32 v6, v28, v116
	v_mul_f32_e32 v7, v29, v116
	v_mul_f32_e32 v21, v30, v116
	v_mul_f32_e32 v24, v31, v116
	v_or_b32_e32 v96, 48, v90
	v_mad_i64_i32 v[28:29], s[2:3], v94, s48, v[22:23]
	global_load_dwordx4 v[28:31], v[28:29], off
	s_waitcnt vmcnt(5)
	v_mul_f32_e32 v1, v32, v118
	v_max3_f32 v3, v3, |v6|, |v1|
	v_mul_f32_e32 v1, v33, v118
	v_max3_f32 v2, v2, |v7|, |v1|
	v_mul_f32_e32 v1, v34, v118
	v_mul_f32_e32 v0, v35, v118
	v_max3_f32 v5, v5, |v21|, |v1|
	v_max3_f32 v4, v4, |v24|, |v0|
	v_mad_i64_i32 v[32:33], s[2:3], v96, s48, v[22:23]
	global_load_dwordx4 v[32:35], v[32:33], off
	v_or_b32_e32 v98, 52, v90
	s_waitcnt vmcnt(5)
	v_mul_f32_e32 v6, v38, v120
	v_mul_f32_e32 v7, v39, v120
	v_mul_f32_e32 v21, v40, v120
	v_mul_f32_e32 v24, v41, v120
	v_mad_i64_i32 v[38:39], s[2:3], v98, s48, v[22:23]
	global_load_dwordx4 v[38:41], v[38:39], off
	v_or_b32_e32 v100, 56, v90
	s_waitcnt vmcnt(5)
	v_mul_f32_e32 v1, v42, v122
	v_max3_f32 v3, v3, |v6|, |v1|
	v_mul_f32_e32 v1, v43, v122
	v_max3_f32 v2, v2, |v7|, |v1|
	v_mul_f32_e32 v1, v44, v122
	v_mul_f32_e32 v0, v45, v122
	v_max3_f32 v5, v5, |v21|, |v1|
	v_max3_f32 v4, v4, |v24|, |v0|
	v_mad_i64_i32 v[42:43], s[2:3], v100, s48, v[22:23]
	global_load_dwordx4 v[42:45], v[42:43], off
	s_waitcnt vmcnt(5)
	v_mul_f32_e32 v6, v46, v124
	v_mul_f32_e32 v7, v47, v124
	v_mul_f32_e32 v21, v48, v124
	v_mul_f32_e32 v24, v49, v124
	s_waitcnt vmcnt(4)
	v_mul_f32_e32 v1, v86, v126
	v_max3_f32 v36, v3, |v6|, |v1|
	v_mul_f32_e32 v1, v87, v126
	v_or_b32_e32 v86, 32, v90
	v_max3_f32 v102, v2, |v7|, |v1|
	v_mul_f32_e32 v1, v88, v126
	v_mul_f32_e32 v0, v89, v126
	v_max3_f32 v21, v5, |v21|, |v1|
	v_max3_f32 v103, v4, |v24|, |v0|
	v_mad_i64_i32 v[0:1], s[2:3], v86, s48, v[22:23]
	global_load_dwordx4 v[0:3], v[0:1], off
	v_or_b32_e32 v88, 36, v90
	v_mad_i64_i32 v[4:5], s[2:3], v88, s48, v[22:23]
	global_load_dwordx4 v[4:7], v[4:5], off
	v_mad_i64_i32 v[24:25], s[2:3], v92, s48, v[22:23]
	global_load_dwordx4 v[24:27], v[24:25], off
	v_or_b32_e32 v90, 60, v90
	v_mad_i64_i32 v[46:47], s[2:3], v90, s48, v[22:23]
	global_load_dwordx4 v[46:49], v[46:47], off
	s_mov_b32 s2, 64
	s_waitcnt vmcnt(3)
	v_mul_f32_e32 v87, v0, v128
	v_mul_f32_e32 v104, v1, v128
	v_mul_f32_e32 v2, v2, v128
	v_mul_f32_e32 v3, v3, v128
	s_waitcnt vmcnt(2)
	v_mul_f32_e32 v1, v4, v130
	v_max3_f32 v4, v36, |v87|, |v1|
	v_mul_f32_e32 v1, v5, v130
	v_max3_f32 v5, v102, |v104|, |v1|
	v_mul_f32_e32 v1, v6, v130
	v_mul_f32_e32 v0, v7, v130
	v_max3_f32 v2, v21, |v2|, |v1|
	v_max3_f32 v3, v103, |v3|, |v0|
	s_waitcnt vmcnt(1)
	v_mul_f32_e32 v6, v24, v132
	v_mul_f32_e32 v7, v25, v132
	v_mul_f32_e32 v21, v26, v132
	v_mul_f32_e32 v24, v27, v132
	v_mul_f32_e32 v1, v28, v134
	v_max3_f32 v4, v4, |v6|, |v1|
	v_mul_f32_e32 v1, v29, v134
	v_max3_f32 v5, v5, |v7|, |v1|
	v_mul_f32_e32 v1, v30, v134
	v_mul_f32_e32 v0, v31, v134
	v_max3_f32 v2, v2, |v21|, |v1|
	v_max3_f32 v3, v3, |v24|, |v0|
	v_mul_f32_e32 v6, v32, v136
	v_mul_f32_e32 v7, v33, v136
	v_mul_f32_e32 v21, v34, v136
	v_mul_f32_e32 v24, v35, v136
	v_mul_f32_e32 v1, v38, v138
	v_max3_f32 v4, v4, |v6|, |v1|
	v_mul_f32_e32 v1, v39, v138
	v_max3_f32 v5, v5, |v7|, |v1|
	v_mul_f32_e32 v1, v40, v138
	v_mul_f32_e32 v0, v41, v138
	v_max3_f32 v6, v2, |v21|, |v1|
	v_max3_f32 v7, v3, |v24|, |v0|
	v_mul_f32_e32 v2, v42, v140
	v_mul_f32_e32 v21, v43, v140
	v_mul_f32_e32 v24, v44, v140
	v_mul_f32_e32 v25, v45, v140
	s_waitcnt vmcnt(0)
	v_mul_f32_e32 v1, v46, v142
	v_max3_f32 v3, v4, |v2|, |v1|
	v_mul_f32_e32 v1, v47, v142
	v_max3_f32 v2, v5, |v21|, |v1|
	v_mul_f32_e32 v1, v48, v142
	v_mul_f32_e32 v0, v49, v142
	v_max3_f32 v1, v6, |v24|, |v1|
	v_max3_f32 v0, v7, |v25|, |v0|
	s_cbranch_vccz .LBB0_1911
	v_and_b32_e32 v5, 64, v159
	v_xor_b32_e32 v4, 16, v159
	v_add_u32_e32 v5, 64, v5
	v_cmp_lt_i32_e32 vcc, v4, v5
	s_nop 1
	v_cndmask_b32_e32 v4, v159, v4, vcc
	v_lshlrev_b32_e32 v6, 2, v4
	ds_bpermute_b32 v7, v6, v3
	v_xor_b32_e32 v4, 32, v159
	v_cmp_lt_i32_e32 vcc, v4, v5
	ds_bpermute_b32 v5, v6, v2
	ds_bpermute_b32 v24, v6, v0
	v_cndmask_b32_e32 v4, v159, v4, vcc
	v_lshlrev_b32_e32 v21, 2, v4
	s_waitcnt lgkmcnt(2)
	v_max_f32_e32 v4, v7, v7
	ds_bpermute_b32 v7, v6, v1
	v_max_f32_e32 v3, v3, v3
	s_waitcnt lgkmcnt(2)
	v_max_f32_e32 v5, v5, v5
	v_max_f32_e32 v2, v2, v2
	v_max_f32_e32 v1, v1, v1
	s_waitcnt lgkmcnt(0)
	v_max_f32_e32 v6, v7, v7
	v_max_f32_e32 v7, v24, v24
	v_max_f32_e32 v0, v0, v0
	v_max_f32_e32 v3, v3, v4
	v_max_f32_e32 v2, v2, v5
	v_max_f32_e32 v1, v1, v6
	v_max_f32_e32 v0, v0, v7
	ds_bpermute_b32 v4, v21, v3
	ds_bpermute_b32 v5, v21, v2
	ds_bpermute_b32 v6, v21, v1
	ds_bpermute_b32 v7, v21, v0
	s_and_saveexec_b64 s[14:15], s[4:5]
	s_cbranch_execz .LBB0_1914
	s_waitcnt lgkmcnt(0)
	v_max_f32_e32 v7, v7, v7
	v_max_f32_e32 v0, v0, v0
	v_max_f32_e32 v7, v0, v7
	v_max_f32_e32 v0, v6, v6
	v_max_f32_e32 v1, v1, v1
	v_max_f32_e32 v6, v1, v0
	v_max_f32_e32 v0, v5, v5
	v_max_f32_e32 v1, v2, v2
	v_max_f32_e32 v5, v1, v0
	v_max_f32_e32 v0, v4, v4
	v_max_f32_e32 v1, v3, v3
	v_max_f32_e32 v4, v1, v0
	v_add_u32_e32 v0, s90, v67
	ds_write_b128 v0, v[4:7]

.LBB0_1921:
	v_or_b32_e32 v108, s0, v85
	v_ashrrev_i32_e32 v109, 31, v108
	v_lshl_add_u64 v[110:111], v[108:109], 2, s[12:13]
	global_load_dword v112, v[110:111], off
	v_or_b32_e32 v108, s0, v85
	v_or_b32_e32 v110, 4, v108
	v_ashrrev_i32_e32 v111, 31, v110
	v_lshl_add_u64 v[108:109], v[110:111], 2, s[12:13]
	global_load_dword v114, v[108:109], off
	v_or_b32_e32 v108, s0, v85
	v_or_b32_e32 v110, 8, v108
	v_ashrrev_i32_e32 v111, 31, v110
	v_lshl_add_u64 v[108:109], v[110:111], 2, s[12:13]
	global_load_dword v116, v[108:109], off
	v_or_b32_e32 v108, s0, v85
	v_or_b32_e32 v110, 12, v108
	v_ashrrev_i32_e32 v111, 31, v110
	v_lshl_add_u64 v[108:109], v[110:111], 2, s[12:13]
	global_load_dword v118, v[108:109], off
	v_or_b32_e32 v108, s0, v85
	v_or_b32_e32 v110, 16, v108
	v_ashrrev_i32_e32 v111, 31, v110
	v_lshl_add_u64 v[108:109], v[110:111], 2, s[12:13]
	global_load_dword v120, v[108:109], off
	v_or_b32_e32 v108, s0, v85
	v_or_b32_e32 v110, 20, v108
	v_ashrrev_i32_e32 v111, 31, v110
	v_lshl_add_u64 v[108:109], v[110:111], 2, s[12:13]
	global_load_dword v122, v[108:109], off
	v_or_b32_e32 v108, s0, v85
	v_or_b32_e32 v110, 24, v108
	v_ashrrev_i32_e32 v111, 31, v110
	v_lshl_add_u64 v[108:109], v[110:111], 2, s[12:13]
	global_load_dword v124, v[108:109], off
	v_or_b32_e32 v108, s0, v85
	v_or_b32_e32 v110, 28, v108
	v_ashrrev_i32_e32 v111, 31, v110
	v_lshl_add_u64 v[108:109], v[110:111], 2, s[12:13]
	global_load_dword v126, v[108:109], off
	v_or_b32_e32 v108, s0, v85
	v_or_b32_e32 v110, 32, v108
	v_ashrrev_i32_e32 v111, 31, v110
	v_lshl_add_u64 v[110:111], v[110:111], 2, s[12:13]
	global_load_dword v128, v[110:111], off
	v_or_b32_e32 v108, s0, v85
	v_or_b32_e32 v110, 36, v108
	v_ashrrev_i32_e32 v111, 31, v110
	v_lshl_add_u64 v[108:109], v[110:111], 2, s[12:13]
	global_load_dword v130, v[108:109], off
	v_or_b32_e32 v108, s0, v85
	v_or_b32_e32 v110, 40, v108
	v_ashrrev_i32_e32 v111, 31, v110
	v_lshl_add_u64 v[108:109], v[110:111], 2, s[12:13]
	global_load_dword v132, v[108:109], off
	v_or_b32_e32 v108, s0, v85
	v_or_b32_e32 v110, 44, v108
	v_ashrrev_i32_e32 v111, 31, v110
	v_lshl_add_u64 v[108:109], v[110:111], 2, s[12:13]
	global_load_dword v134, v[108:109], off
	v_or_b32_e32 v108, s0, v85
	v_or_b32_e32 v110, 48, v108
	v_ashrrev_i32_e32 v111, 31, v110
	v_lshl_add_u64 v[108:109], v[110:111], 2, s[12:13]
	global_load_dword v136, v[108:109], off
	v_or_b32_e32 v108, s0, v85
	v_or_b32_e32 v110, 52, v108
	v_ashrrev_i32_e32 v111, 31, v110
	v_lshl_add_u64 v[108:109], v[110:111], 2, s[12:13]
	global_load_dword v138, v[108:109], off
	v_or_b32_e32 v108, s0, v85
	v_or_b32_e32 v110, 56, v108
	v_ashrrev_i32_e32 v111, 31, v110
	v_lshl_add_u64 v[108:109], v[110:111], 2, s[12:13]
	global_load_dword v140, v[108:109], off
	v_or_b32_e32 v108, s0, v85
	v_or_b32_e32 v108, 60, v108
	v_ashrrev_i32_e32 v109, 31, v108
	v_lshl_add_u64 v[110:111], v[108:109], 2, s[12:13]
	global_load_dword v142, v[110:111], off
	v_or_b32_e32 v90, s0, v85
	s_andn2_b64 vcc, exec, s[14:15]
	v_mad_i64_i32 v[4:5], s[0:1], v90, s55, v[22:23]
	global_load_dwordx4 v[4:7], v[4:5], off
	v_or_b32_e32 v92, 4, v90
	v_mad_i64_i32 v[24:25], s[0:1], v92, s55, v[22:23]
	global_load_dwordx4 v[24:27], v[24:25], off
	v_or_b32_e32 v94, 8, v90
	v_mad_i64_i32 v[28:29], s[0:1], v94, s55, v[22:23]
	global_load_dwordx4 v[28:31], v[28:29], off
	v_or_b32_e32 v96, 12, v90
	v_mad_i64_i32 v[32:33], s[0:1], v96, s55, v[22:23]
	global_load_dwordx4 v[32:35], v[32:33], off
	v_or_b32_e32 v98, 16, v90
	v_mad_i64_i32 v[38:39], s[0:1], v98, s55, v[22:23]
	global_load_dwordx4 v[38:41], v[38:39], off
	v_or_b32_e32 v100, 20, v90
	v_mad_i64_i32 v[42:43], s[0:1], v100, s55, v[22:23]
	global_load_dwordx4 v[42:45], v[42:43], off
	v_or_b32_e32 v102, 24, v90
	v_mad_i64_i32 v[46:47], s[0:1], v102, s55, v[22:23]
	global_load_dwordx4 v[46:49], v[46:47], off
	v_or_b32_e32 v104, 28, v90
	v_mad_i64_i32 v[86:87], s[0:1], v104, s55, v[22:23]
	global_load_dwordx4 v[86:89], v[86:87], off
	s_mov_b64 s[14:15], 0
	s_and_b64 vcc, exec, vcc
	s_waitcnt vmcnt(7)
	v_mul_f32_e32 v36, v4, v112
	v_mul_f32_e32 v91, v5, v112
	v_mul_f32_e32 v6, v6, v112
	v_mul_f32_e32 v7, v7, v112
	v_or_b32_e32 v92, 40, v90
	s_waitcnt vmcnt(6)
	v_mul_f32_e32 v5, v24, v114
	v_max3_f32 v3, v3, |v36|, |v5|
	v_mul_f32_e32 v5, v25, v114
	v_max3_f32 v2, v2, |v91|, |v5|
	v_mul_f32_e32 v5, v26, v114
	v_max3_f32 v5, v1, |v6|, |v5|
	v_mul_f32_e32 v1, v27, v114
	v_max3_f32 v4, v0, |v7|, |v1|
	v_or_b32_e32 v94, 44, v90
	s_waitcnt vmcnt(5)
	v_mul_f32_e32 v6, v28, v116
	v_mul_f32_e32 v7, v29, v116
	v_mul_f32_e32 v21, v30, v116
	v_mul_f32_e32 v24, v31, v116
	v_or_b32_e32 v96, 48, v90
	v_mad_i64_i32 v[28:29], s[0:1], v94, s55, v[22:23]
	global_load_dwordx4 v[28:31], v[28:29], off
	s_waitcnt vmcnt(5)
	v_mul_f32_e32 v1, v32, v118
	v_max3_f32 v3, v3, |v6|, |v1|
	v_mul_f32_e32 v1, v33, v118
	v_max3_f32 v2, v2, |v7|, |v1|
	v_mul_f32_e32 v1, v34, v118
	v_mul_f32_e32 v0, v35, v118
	v_max3_f32 v5, v5, |v21|, |v1|
	v_max3_f32 v4, v4, |v24|, |v0|
	v_mad_i64_i32 v[32:33], s[0:1], v96, s55, v[22:23]
	global_load_dwordx4 v[32:35], v[32:33], off
	v_or_b32_e32 v98, 52, v90
	s_waitcnt vmcnt(5)
	v_mul_f32_e32 v6, v38, v120
	v_mul_f32_e32 v7, v39, v120
	v_mul_f32_e32 v21, v40, v120
	v_mul_f32_e32 v24, v41, v120
	v_mad_i64_i32 v[38:39], s[0:1], v98, s55, v[22:23]
	global_load_dwordx4 v[38:41], v[38:39], off
	v_or_b32_e32 v100, 56, v90
	s_waitcnt vmcnt(5)
	v_mul_f32_e32 v1, v42, v122
	v_max3_f32 v3, v3, |v6|, |v1|
	v_mul_f32_e32 v1, v43, v122
	v_max3_f32 v2, v2, |v7|, |v1|
	v_mul_f32_e32 v1, v44, v122
	v_mul_f32_e32 v0, v45, v122
	v_max3_f32 v5, v5, |v21|, |v1|
	v_max3_f32 v4, v4, |v24|, |v0|
	v_mad_i64_i32 v[42:43], s[0:1], v100, s55, v[22:23]
	global_load_dwordx4 v[42:45], v[42:43], off
	s_waitcnt vmcnt(5)
	v_mul_f32_e32 v6, v46, v124
	v_mul_f32_e32 v7, v47, v124
	v_mul_f32_e32 v21, v48, v124
	v_mul_f32_e32 v24, v49, v124
	s_waitcnt vmcnt(4)
	v_mul_f32_e32 v1, v86, v126
	v_max3_f32 v36, v3, |v6|, |v1|
	v_mul_f32_e32 v1, v87, v126
	v_or_b32_e32 v86, 32, v90
	v_max3_f32 v102, v2, |v7|, |v1|
	v_mul_f32_e32 v1, v88, v126
	v_mul_f32_e32 v0, v89, v126
	v_max3_f32 v21, v5, |v21|, |v1|
	v_max3_f32 v103, v4, |v24|, |v0|
	v_mad_i64_i32 v[0:1], s[0:1], v86, s55, v[22:23]
	global_load_dwordx4 v[0:3], v[0:1], off
	v_or_b32_e32 v88, 36, v90
	v_mad_i64_i32 v[4:5], s[0:1], v88, s55, v[22:23]
	global_load_dwordx4 v[4:7], v[4:5], off
	v_mad_i64_i32 v[24:25], s[0:1], v92, s55, v[22:23]
	global_load_dwordx4 v[24:27], v[24:25], off
	v_or_b32_e32 v90, 60, v90
	v_mad_i64_i32 v[46:47], s[0:1], v90, s55, v[22:23]
	global_load_dwordx4 v[46:49], v[46:47], off
	s_mov_b32 s0, 64
	s_waitcnt vmcnt(3)
	v_mul_f32_e32 v87, v0, v128
	v_mul_f32_e32 v104, v1, v128
	v_mul_f32_e32 v2, v2, v128
	v_mul_f32_e32 v3, v3, v128
	s_waitcnt vmcnt(2)
	v_mul_f32_e32 v1, v4, v130
	v_max3_f32 v4, v36, |v87|, |v1|
	v_mul_f32_e32 v1, v5, v130
	v_max3_f32 v5, v102, |v104|, |v1|
	v_mul_f32_e32 v1, v6, v130
	v_mul_f32_e32 v0, v7, v130
	v_max3_f32 v2, v21, |v2|, |v1|
	v_max3_f32 v3, v103, |v3|, |v0|
	s_waitcnt vmcnt(1)
	v_mul_f32_e32 v6, v24, v132
	v_mul_f32_e32 v7, v25, v132
	v_mul_f32_e32 v21, v26, v132
	v_mul_f32_e32 v24, v27, v132
	v_mul_f32_e32 v1, v28, v134
	v_max3_f32 v4, v4, |v6|, |v1|
	v_mul_f32_e32 v1, v29, v134
	v_max3_f32 v5, v5, |v7|, |v1|
	v_mul_f32_e32 v1, v30, v134
	v_mul_f32_e32 v0, v31, v134
	v_max3_f32 v2, v2, |v21|, |v1|
	v_max3_f32 v3, v3, |v24|, |v0|
	v_mul_f32_e32 v6, v32, v136
	v_mul_f32_e32 v7, v33, v136
	v_mul_f32_e32 v21, v34, v136
	v_mul_f32_e32 v24, v35, v136
	v_mul_f32_e32 v1, v38, v138
	v_max3_f32 v4, v4, |v6|, |v1|
	v_mul_f32_e32 v1, v39, v138
	v_max3_f32 v5, v5, |v7|, |v1|
	v_mul_f32_e32 v1, v40, v138
	v_mul_f32_e32 v0, v41, v138
	v_max3_f32 v6, v2, |v21|, |v1|
	v_max3_f32 v7, v3, |v24|, |v0|
	v_mul_f32_e32 v2, v42, v140
	v_mul_f32_e32 v21, v43, v140
	v_mul_f32_e32 v24, v44, v140
	v_mul_f32_e32 v25, v45, v140
	s_waitcnt vmcnt(0)
	v_mul_f32_e32 v1, v46, v142
	v_max3_f32 v3, v4, |v2|, |v1|
	v_mul_f32_e32 v1, v47, v142
	v_max3_f32 v2, v5, |v21|, |v1|
	v_mul_f32_e32 v1, v48, v142
	v_mul_f32_e32 v0, v49, v142
	v_max3_f32 v1, v6, |v24|, |v1|
	v_max3_f32 v0, v7, |v25|, |v0|
	s_cbranch_vccz .LBB0_1921
	v_and_b32_e32 v5, 64, v159
	v_xor_b32_e32 v4, 16, v159
	v_add_u32_e32 v5, 64, v5
	v_cmp_lt_i32_e32 vcc, v4, v5
	s_nop 1
	v_cndmask_b32_e32 v4, v159, v4, vcc
	v_lshlrev_b32_e32 v6, 2, v4
	ds_bpermute_b32 v7, v6, v3
	v_xor_b32_e32 v4, 32, v159
	v_cmp_lt_i32_e32 vcc, v4, v5
	ds_bpermute_b32 v5, v6, v2
	ds_bpermute_b32 v24, v6, v0
	v_cndmask_b32_e32 v4, v159, v4, vcc
	v_lshlrev_b32_e32 v21, 2, v4
	s_waitcnt lgkmcnt(2)
	v_max_f32_e32 v4, v7, v7
	ds_bpermute_b32 v7, v6, v1
	v_max_f32_e32 v3, v3, v3
	s_waitcnt lgkmcnt(2)
	v_max_f32_e32 v5, v5, v5
	v_max_f32_e32 v2, v2, v2
	v_max_f32_e32 v1, v1, v1
	s_waitcnt lgkmcnt(0)
	v_max_f32_e32 v6, v7, v7
	v_max_f32_e32 v7, v24, v24
	v_max_f32_e32 v0, v0, v0
	v_max_f32_e32 v3, v3, v4
	v_max_f32_e32 v2, v2, v5
	v_max_f32_e32 v1, v1, v6
	v_max_f32_e32 v0, v0, v7
	ds_bpermute_b32 v4, v21, v3
	ds_bpermute_b32 v5, v21, v2
	ds_bpermute_b32 v6, v21, v1
	ds_bpermute_b32 v7, v21, v0
	s_and_saveexec_b64 s[14:15], s[4:5]
	s_cbranch_execz .LBB0_1924
	s_waitcnt lgkmcnt(0)
	v_max_f32_e32 v7, v7, v7
	v_max_f32_e32 v0, v0, v0
	v_max_f32_e32 v7, v0, v7
	v_max_f32_e32 v0, v6, v6
	v_max_f32_e32 v1, v1, v1
	v_max_f32_e32 v6, v1, v0
	v_max_f32_e32 v0, v5, v5
	v_max_f32_e32 v1, v2, v2
	v_max_f32_e32 v5, v1, v0
	v_max_f32_e32 v0, v4, v4
	v_max_f32_e32 v1, v3, v3
	v_max_f32_e32 v4, v1, v0
	v_add_u32_e32 v0, s90, v67
	ds_write_b128 v0, v[4:7]

.LBB0_1945:
	v_or_b32_e32 v108, s1, v85
	v_ashrrev_i32_e32 v109, 31, v108
	v_lshl_add_u64 v[110:111], v[108:109], 2, s[12:13]
	global_load_dword v112, v[110:111], off
	v_or_b32_e32 v108, s1, v85
	v_or_b32_e32 v110, 4, v108
	v_ashrrev_i32_e32 v111, 31, v110
	v_lshl_add_u64 v[108:109], v[110:111], 2, s[12:13]
	global_load_dword v114, v[108:109], off
	v_or_b32_e32 v108, s1, v85
	v_or_b32_e32 v110, 8, v108
	v_ashrrev_i32_e32 v111, 31, v110
	v_lshl_add_u64 v[108:109], v[110:111], 2, s[12:13]
	global_load_dword v116, v[108:109], off
	v_or_b32_e32 v108, s1, v85
	v_or_b32_e32 v110, 12, v108
	v_ashrrev_i32_e32 v111, 31, v110
	v_lshl_add_u64 v[108:109], v[110:111], 2, s[12:13]
	global_load_dword v118, v[108:109], off
	v_or_b32_e32 v108, s1, v85
	v_or_b32_e32 v110, 16, v108
	v_ashrrev_i32_e32 v111, 31, v110
	v_lshl_add_u64 v[108:109], v[110:111], 2, s[12:13]
	global_load_dword v120, v[108:109], off
	v_or_b32_e32 v108, s1, v85
	v_or_b32_e32 v110, 20, v108
	v_ashrrev_i32_e32 v111, 31, v110
	v_lshl_add_u64 v[108:109], v[110:111], 2, s[12:13]
	global_load_dword v122, v[108:109], off
	v_or_b32_e32 v108, s1, v85
	v_or_b32_e32 v110, 24, v108
	v_ashrrev_i32_e32 v111, 31, v110
	v_lshl_add_u64 v[108:109], v[110:111], 2, s[12:13]
	global_load_dword v124, v[108:109], off
	v_or_b32_e32 v108, s1, v85
	v_or_b32_e32 v110, 28, v108
	v_ashrrev_i32_e32 v111, 31, v110
	v_lshl_add_u64 v[108:109], v[110:111], 2, s[12:13]
	global_load_dword v126, v[108:109], off
	v_or_b32_e32 v108, s1, v85
	v_or_b32_e32 v110, 32, v108
	v_ashrrev_i32_e32 v111, 31, v110
	v_lshl_add_u64 v[110:111], v[110:111], 2, s[12:13]
	global_load_dword v128, v[110:111], off
	v_or_b32_e32 v108, s1, v85
	v_or_b32_e32 v110, 36, v108
	v_ashrrev_i32_e32 v111, 31, v110
	v_lshl_add_u64 v[108:109], v[110:111], 2, s[12:13]
	global_load_dword v130, v[108:109], off
	v_or_b32_e32 v108, s1, v85
	v_or_b32_e32 v110, 40, v108
	v_ashrrev_i32_e32 v111, 31, v110
	v_lshl_add_u64 v[108:109], v[110:111], 2, s[12:13]
	global_load_dword v132, v[108:109], off
	v_or_b32_e32 v108, s1, v85
	v_or_b32_e32 v110, 44, v108
	v_ashrrev_i32_e32 v111, 31, v110
	v_lshl_add_u64 v[108:109], v[110:111], 2, s[12:13]
	global_load_dword v134, v[108:109], off
	v_or_b32_e32 v108, s1, v85
	v_or_b32_e32 v110, 48, v108
	v_ashrrev_i32_e32 v111, 31, v110
	v_lshl_add_u64 v[108:109], v[110:111], 2, s[12:13]
	global_load_dword v136, v[108:109], off
	v_or_b32_e32 v108, s1, v85
	v_or_b32_e32 v110, 52, v108
	v_ashrrev_i32_e32 v111, 31, v110
	v_lshl_add_u64 v[108:109], v[110:111], 2, s[12:13]
	global_load_dword v138, v[108:109], off
	v_or_b32_e32 v108, s1, v85
	v_or_b32_e32 v110, 56, v108
	v_ashrrev_i32_e32 v111, 31, v110
	v_lshl_add_u64 v[108:109], v[110:111], 2, s[12:13]
	global_load_dword v140, v[108:109], off
	v_or_b32_e32 v108, s1, v85
	v_or_b32_e32 v108, 60, v108
	v_ashrrev_i32_e32 v109, 31, v108
	v_lshl_add_u64 v[110:111], v[108:109], 2, s[12:13]
	global_load_dword v142, v[110:111], off
	v_or_b32_e32 v90, s1, v85
	s_andn2_b64 vcc, exec, s[14:15]
	v_mad_i64_i32 v[4:5], s[2:3], v90, s55, v[22:23]
	global_load_dwordx4 v[4:7], v[4:5], off
	v_or_b32_e32 v92, 4, v90
	v_mad_i64_i32 v[24:25], s[2:3], v92, s55, v[22:23]
	global_load_dwordx4 v[24:27], v[24:25], off
	v_or_b32_e32 v94, 8, v90
	v_mad_i64_i32 v[28:29], s[2:3], v94, s55, v[22:23]
	global_load_dwordx4 v[28:31], v[28:29], off
	v_or_b32_e32 v96, 12, v90
	v_mad_i64_i32 v[32:33], s[2:3], v96, s55, v[22:23]
	global_load_dwordx4 v[32:35], v[32:33], off
	v_or_b32_e32 v98, 16, v90
	v_mad_i64_i32 v[38:39], s[2:3], v98, s55, v[22:23]
	global_load_dwordx4 v[38:41], v[38:39], off
	v_or_b32_e32 v100, 20, v90
	v_mad_i64_i32 v[42:43], s[2:3], v100, s55, v[22:23]
	global_load_dwordx4 v[42:45], v[42:43], off
	v_or_b32_e32 v102, 24, v90
	v_mad_i64_i32 v[46:47], s[2:3], v102, s55, v[22:23]
	global_load_dwordx4 v[46:49], v[46:47], off
	v_or_b32_e32 v104, 28, v90
	v_mad_i64_i32 v[86:87], s[2:3], v104, s55, v[22:23]
	global_load_dwordx4 v[86:89], v[86:87], off
	s_mov_b32 s1, 64
	s_mov_b64 s[14:15], 0
	s_and_b64 vcc, exec, vcc
	s_waitcnt vmcnt(7)
	v_mul_f32_e32 v36, v4, v112
	v_mul_f32_e32 v91, v5, v112
	v_mul_f32_e32 v6, v6, v112
	v_mul_f32_e32 v7, v7, v112
	v_or_b32_e32 v92, 40, v90
	s_waitcnt vmcnt(6)
	v_mul_f32_e32 v5, v24, v114
	v_max3_f32 v3, v3, |v36|, |v5|
	v_mul_f32_e32 v5, v25, v114
	v_max3_f32 v2, v2, |v91|, |v5|
	v_mul_f32_e32 v5, v26, v114
	v_max3_f32 v5, v1, |v6|, |v5|
	v_mul_f32_e32 v1, v27, v114
	v_max3_f32 v4, v0, |v7|, |v1|
	v_or_b32_e32 v94, 44, v90
	s_waitcnt vmcnt(5)
	v_mul_f32_e32 v6, v28, v116
	v_mul_f32_e32 v7, v29, v116
	v_mul_f32_e32 v21, v30, v116
	v_mul_f32_e32 v24, v31, v116
	v_or_b32_e32 v96, 48, v90
	v_mad_i64_i32 v[28:29], s[2:3], v94, s55, v[22:23]
	global_load_dwordx4 v[28:31], v[28:29], off
	s_waitcnt vmcnt(5)
	v_mul_f32_e32 v1, v32, v118
	v_max3_f32 v3, v3, |v6|, |v1|
	v_mul_f32_e32 v1, v33, v118
	v_max3_f32 v2, v2, |v7|, |v1|
	v_mul_f32_e32 v1, v34, v118
	v_mul_f32_e32 v0, v35, v118
	v_max3_f32 v5, v5, |v21|, |v1|
	v_max3_f32 v4, v4, |v24|, |v0|
	v_mad_i64_i32 v[32:33], s[2:3], v96, s55, v[22:23]
	global_load_dwordx4 v[32:35], v[32:33], off
	v_or_b32_e32 v98, 52, v90
	s_waitcnt vmcnt(5)
	v_mul_f32_e32 v6, v38, v120
	v_mul_f32_e32 v7, v39, v120
	v_mul_f32_e32 v21, v40, v120
	v_mul_f32_e32 v24, v41, v120
	v_mad_i64_i32 v[38:39], s[2:3], v98, s55, v[22:23]
	global_load_dwordx4 v[38:41], v[38:39], off
	v_or_b32_e32 v100, 56, v90
	s_waitcnt vmcnt(5)
	v_mul_f32_e32 v1, v42, v122
	v_max3_f32 v3, v3, |v6|, |v1|
	v_mul_f32_e32 v1, v43, v122
	v_max3_f32 v2, v2, |v7|, |v1|
	v_mul_f32_e32 v1, v44, v122
	v_mul_f32_e32 v0, v45, v122
	v_max3_f32 v5, v5, |v21|, |v1|
	v_max3_f32 v4, v4, |v24|, |v0|
	v_mad_i64_i32 v[42:43], s[2:3], v100, s55, v[22:23]
	global_load_dwordx4 v[42:45], v[42:43], off
	s_waitcnt vmcnt(5)
	v_mul_f32_e32 v6, v46, v124
	v_mul_f32_e32 v7, v47, v124
	v_mul_f32_e32 v21, v48, v124
	v_mul_f32_e32 v24, v49, v124
	s_waitcnt vmcnt(4)
	v_mul_f32_e32 v1, v86, v126
	v_max3_f32 v36, v3, |v6|, |v1|
	v_mul_f32_e32 v1, v87, v126
	v_or_b32_e32 v86, 32, v90
	v_max3_f32 v102, v2, |v7|, |v1|
	v_mul_f32_e32 v1, v88, v126
	v_mul_f32_e32 v0, v89, v126
	v_max3_f32 v21, v5, |v21|, |v1|
	v_max3_f32 v103, v4, |v24|, |v0|
	v_mad_i64_i32 v[0:1], s[2:3], v86, s55, v[22:23]
	global_load_dwordx4 v[0:3], v[0:1], off
	v_or_b32_e32 v88, 36, v90
	v_mad_i64_i32 v[4:5], s[2:3], v88, s55, v[22:23]
	global_load_dwordx4 v[4:7], v[4:5], off
	v_mad_i64_i32 v[24:25], s[2:3], v92, s55, v[22:23]
	global_load_dwordx4 v[24:27], v[24:25], off
	v_or_b32_e32 v90, 60, v90
	v_mad_i64_i32 v[46:47], s[2:3], v90, s55, v[22:23]
	global_load_dwordx4 v[46:49], v[46:47], off
	s_waitcnt vmcnt(3)
	v_mul_f32_e32 v87, v0, v128
	v_mul_f32_e32 v104, v1, v128
	v_mul_f32_e32 v2, v2, v128
	v_mul_f32_e32 v3, v3, v128
	s_waitcnt vmcnt(2)
	v_mul_f32_e32 v1, v4, v130
	v_max3_f32 v4, v36, |v87|, |v1|
	v_mul_f32_e32 v1, v5, v130
	v_max3_f32 v5, v102, |v104|, |v1|
	v_mul_f32_e32 v1, v6, v130
	v_mul_f32_e32 v0, v7, v130
	v_max3_f32 v2, v21, |v2|, |v1|
	v_max3_f32 v3, v103, |v3|, |v0|
	s_waitcnt vmcnt(1)
	v_mul_f32_e32 v6, v24, v132
	v_mul_f32_e32 v7, v25, v132
	v_mul_f32_e32 v21, v26, v132
	v_mul_f32_e32 v24, v27, v132
	v_mul_f32_e32 v1, v28, v134
	v_max3_f32 v4, v4, |v6|, |v1|
	v_mul_f32_e32 v1, v29, v134
	v_max3_f32 v5, v5, |v7|, |v1|
	v_mul_f32_e32 v1, v30, v134
	v_mul_f32_e32 v0, v31, v134
	v_max3_f32 v2, v2, |v21|, |v1|
	v_max3_f32 v3, v3, |v24|, |v0|
	v_mul_f32_e32 v6, v32, v136
	v_mul_f32_e32 v7, v33, v136
	v_mul_f32_e32 v21, v34, v136
	v_mul_f32_e32 v24, v35, v136
	v_mul_f32_e32 v1, v38, v138
	v_max3_f32 v4, v4, |v6|, |v1|
	v_mul_f32_e32 v1, v39, v138
	v_max3_f32 v5, v5, |v7|, |v1|
	v_mul_f32_e32 v1, v40, v138
	v_mul_f32_e32 v0, v41, v138
	v_max3_f32 v6, v2, |v21|, |v1|
	v_max3_f32 v7, v3, |v24|, |v0|
	v_mul_f32_e32 v2, v42, v140
	v_mul_f32_e32 v21, v43, v140
	v_mul_f32_e32 v24, v44, v140
	v_mul_f32_e32 v25, v45, v140
	s_waitcnt vmcnt(0)
	v_mul_f32_e32 v1, v46, v142
	v_max3_f32 v3, v4, |v2|, |v1|
	v_mul_f32_e32 v1, v47, v142
	v_max3_f32 v2, v5, |v21|, |v1|
	v_mul_f32_e32 v1, v48, v142
	v_mul_f32_e32 v0, v49, v142
	v_max3_f32 v1, v6, |v24|, |v1|
	v_max3_f32 v0, v7, |v25|, |v0|
	s_cbranch_vccz .LBB0_1945
	v_and_b32_e32 v5, 64, v159
	v_xor_b32_e32 v4, 16, v159
	v_add_u32_e32 v5, 64, v5
	v_cmp_lt_i32_e32 vcc, v4, v5
	s_nop 1
	v_cndmask_b32_e32 v4, v159, v4, vcc
	v_lshlrev_b32_e32 v6, 2, v4
	ds_bpermute_b32 v7, v6, v3
	v_xor_b32_e32 v4, 32, v159
	v_cmp_lt_i32_e32 vcc, v4, v5
	ds_bpermute_b32 v5, v6, v2
	ds_bpermute_b32 v24, v6, v0
	v_cndmask_b32_e32 v4, v159, v4, vcc
	v_lshlrev_b32_e32 v21, 2, v4
	s_waitcnt lgkmcnt(2)
	v_max_f32_e32 v4, v7, v7
	ds_bpermute_b32 v7, v6, v1
	v_max_f32_e32 v3, v3, v3
	s_waitcnt lgkmcnt(2)
	v_max_f32_e32 v5, v5, v5
	v_max_f32_e32 v2, v2, v2
	v_max_f32_e32 v1, v1, v1
	s_waitcnt lgkmcnt(0)
	v_max_f32_e32 v6, v7, v7
	v_max_f32_e32 v7, v24, v24
	v_max_f32_e32 v0, v0, v0
	v_max_f32_e32 v3, v3, v4
	v_max_f32_e32 v2, v2, v5
	v_max_f32_e32 v1, v1, v6
	v_max_f32_e32 v0, v0, v7
	ds_bpermute_b32 v4, v21, v3
	ds_bpermute_b32 v5, v21, v2
	ds_bpermute_b32 v6, v21, v1
	ds_bpermute_b32 v7, v21, v0
	s_and_saveexec_b64 s[14:15], s[4:5]
	s_cbranch_execz .LBB0_1948
	s_waitcnt lgkmcnt(0)
	v_max_f32_e32 v7, v7, v7
	v_max_f32_e32 v0, v0, v0
	v_max_f32_e32 v7, v0, v7
	v_max_f32_e32 v0, v6, v6
	v_max_f32_e32 v1, v1, v1
	v_max_f32_e32 v6, v1, v0
	v_max_f32_e32 v0, v5, v5
	v_max_f32_e32 v1, v2, v2
	v_max_f32_e32 v5, v1, v0
	v_max_f32_e32 v0, v4, v4
	v_max_f32_e32 v1, v3, v3
	v_max_f32_e32 v4, v1, v0
	v_add_u32_e32 v0, s90, v67
	ds_write_b128 v0, v[4:7]

.LBB0_2139:
	v_pk_mul_f32 v[104:105], v[104:105], v[172:173] op_sel_hi:[1,0]
	v_pk_mul_f32 v[110:111], v[110:111], v[172:173] op_sel_hi:[1,0]
	v_pk_mul_f32 v[108:109], v[108:109], v[172:173] op_sel_hi:[1,0]
	v_pk_mul_f32 v[106:107], v[106:107], v[172:173] op_sel_hi:[1,0]
	v_pk_mul_f32 v[102:103], v[102:103], v[172:173] op_sel_hi:[1,0]
	v_pk_mul_f32 v[100:101], v[100:101], v[172:173] op_sel_hi:[1,0]
	v_pk_mul_f32 v[112:113], v[98:99], v[172:173] op_sel_hi:[1,0]
	v_pk_mul_f32 v[114:115], v[96:97], v[172:173] op_sel_hi:[1,0]
	v_cvt_pk_bf16_f32 v98, v104, v105
	v_cvt_pk_bf16_f32 v96, v108, v109
	v_cvt_pk_bf16_f32 v97, v110, v111
	v_cvt_pk_bf16_f32 v99, v106, v107
	v_cvt_pk_bf16_f32 v100, v100, v101
	v_cvt_pk_bf16_f32 v101, v102, v103
	v_cvt_pk_bf16_f32 v102, v114, v115
	v_cvt_pk_bf16_f32 v103, v112, v113
	v_ashrrev_i32_e32 v177, 31, v176
	s_andn2_b64 s[6:7], exec, s[8:9]
	s_andn2_b64 vcc, exec, s[8:9]
	s_mov_b64 s[8:9], -1
	s_cbranch_vccnz .LBB0_2141
	v_mul_lo_u32 v106, s65, v176
	v_mul_lo_u32 v107, s64, v177
	v_mad_u64_u32 v[104:105], s[8:9], s64, v176, 0
	v_add3_u32 v105, v105, v107, v106
	v_lshl_add_u64 v[104:105], v[104:105], 1, v[174:175]
	s_mov_b64 s[8:9], 0
	global_store_dwordx4 v[104:105], v[96:99], off
	global_store_dwordx4 v[104:105], v[100:103], off offset:64

.LBB0_2220:
	v_mov_b32_e32 v0, v179
	v_pk_mul_f32 v[2:3], v[0:1], v[116:117] op_sel_hi:[0,1]
	v_pk_mul_f32 v[12:13], v[0:1], v[112:113] op_sel_hi:[0,1]
	v_pk_mul_f32 v[4:5], v[0:1], v[114:115] op_sel_hi:[0,1]
	v_pk_mul_f32 v[6:7], v[0:1], v[118:119] op_sel_hi:[0,1]
	v_pk_mul_f32 v[14:15], v[0:1], v[184:185] op_sel_hi:[0,1]
	v_pk_mul_f32 v[112:113], v[0:1], v[182:183] op_sel_hi:[0,1]
	v_pk_mul_f32 v[114:115], v[0:1], v[186:187] op_sel_hi:[0,1]
	v_pk_mul_f32 v[116:117], v[0:1], v[180:181] op_sel_hi:[0,1]
	v_cvt_pk_bf16_f32 v1, v2, v3
	v_cvt_pk_bf16_f32 v2, v12, v13
	v_cvt_pk_bf16_f32 v0, v4, v5
	v_cvt_pk_bf16_f32 v3, v6, v7
	v_cvt_pk_bf16_f32 v4, v112, v113
	v_cvt_pk_bf16_f32 v5, v14, v15
	v_cvt_pk_bf16_f32 v6, v116, v117
	v_cvt_pk_bf16_f32 v7, v114, v115
	v_ashrrev_i32_e32 v133, 31, v132
	s_andn2_b64 s[6:7], exec, s[48:49]
	s_andn2_b64 vcc, exec, s[48:49]
	s_mov_b64 s[48:49], -1
	s_cbranch_vccnz .LBB0_2222
	v_mul_lo_u32 v14, s69, v132
	v_mul_lo_u32 v15, s68, v133
	v_mad_u64_u32 v[12:13], s[48:49], s68, v132, 0
	v_add3_u32 v13, v13, v15, v14
	v_lshl_add_u64 v[12:13], v[12:13], 1, v[8:9]
	s_mov_b64 s[48:49], 0
	global_store_dwordx4 v[12:13], v[0:3], off
	global_store_dwordx4 v[12:13], v[4:7], off offset:64

.LBB0_2286:
	s_lshl_b32 s29, s22, 10
	s_sub_i32 s5, s9, s29
	v_add_u32_e32 v50, s5, v221
	s_ashr_i32 s5, s4, 31
	v_lshl_add_u64 v[0:1], s[4:5], 2, v[44:45]
	v_mad_i64_i32 v[2:3], s[4:5], v50, s85, v[0:1]
	s_mul_i32 s4, s22, 0xfe500000
	s_nop 0
	v_add_u32_e32 v4, s4, v64
	v_ashrrev_i32_e32 v5, 31, v4
	v_lshl_add_u64 v[52:53], v[0:1], 0, v[4:5]
	s_mov_b32 s4, 0x1b000
	v_add_co_u32_e32 v0, vcc, s4, v52
	s_mov_b32 s4, 0x36000
	s_nop 0
	v_addc_co_u32_e32 v1, vcc, 0, v53, vcc
	global_load_dwordx4 v[24:27], v[2:3], off nt
	global_load_dwordx4 v[28:31], v[0:1], off nt
	v_add_co_u32_e32 v0, vcc, s4, v52
	s_mov_b32 s4, 0x51000
	s_nop 0
	v_addc_co_u32_e32 v1, vcc, 0, v53, vcc
	v_add_co_u32_e32 v2, vcc, s4, v52
	s_mov_b32 s4, 0x6c000
	s_nop 0
	v_addc_co_u32_e32 v3, vcc, 0, v53, vcc
	global_load_dwordx4 v[16:19], v[0:1], off nt
	global_load_dwordx4 v[20:23], v[2:3], off nt
	v_add_co_u32_e32 v0, vcc, s4, v52
	s_nop 0
	s_nop 0
	v_addc_co_u32_e32 v1, vcc, 0, v53, vcc
	v_add_co_u32_e32 v2, vcc, 0x87000, v52
	s_andn2_b64 s[4:5], exec, s[16:17]
	s_nop 0
	v_addc_co_u32_e32 v3, vcc, 0, v53, vcc
	global_load_dwordx4 v[8:11], v[0:1], off nt
	global_load_dwordx4 v[12:15], v[2:3], off nt
	v_add_co_u32_e32 v0, vcc, 0xa2000, v52
	v_ashrrev_i32_e32 v51, 31, v50
	s_nop 0
	v_addc_co_u32_e32 v1, vcc, 0, v53, vcc
	v_add_co_u32_e32 v4, vcc, 0xbd000, v52
	s_nop 1
	v_addc_co_u32_e32 v5, vcc, 0, v53, vcc
	global_load_dwordx4 v[0:3], v[0:1], off nt
	s_nop 0
	global_load_dwordx4 v[4:7], v[4:5], off nt
	s_andn2_b64 vcc, exec, s[16:17]
	s_cbranch_vccnz .LBB0_2309
	v_add_u32_e32 v34, 4, v50
	v_lshl_add_u64 v[32:33], v[50:51], 2, s[14:15]
	v_ashrrev_i32_e32 v35, 31, v34
	global_load_dword v32, v[32:33], off
	v_lshl_add_u64 v[34:35], v[34:35], 2, s[14:15]
	global_load_dword v70, v[34:35], off
	s_waitcnt vmcnt(1)
	v_pk_mul_f32 v[34:35], v[26:27], v[32:33] op_sel_hi:[1,0]
	v_pk_mul_f32 v[32:33], v[24:25], v[32:33] op_sel_hi:[1,0]
	ds_write2_b32 v54, v32, v33 offset1:1
	ds_write2_b32 v54, v34, v35 offset0:2 offset1:3
	s_waitcnt vmcnt(0)
	v_pk_mul_f32 v[34:35], v[30:31], v[70:71] op_sel_hi:[1,0]
	v_pk_mul_f32 v[32:33], v[28:29], v[70:71] op_sel_hi:[1,0]
	s_cbranch_execnz .LBB0_2289

.LBB0_2551:
	v_pk_mul_f32 v[104:105], v[104:105], v[172:173] op_sel_hi:[1,0]
	v_pk_mul_f32 v[110:111], v[110:111], v[172:173] op_sel_hi:[1,0]
	v_pk_mul_f32 v[108:109], v[108:109], v[172:173] op_sel_hi:[1,0]
	v_pk_mul_f32 v[106:107], v[106:107], v[172:173] op_sel_hi:[1,0]
	v_pk_mul_f32 v[102:103], v[102:103], v[172:173] op_sel_hi:[1,0]
	v_pk_mul_f32 v[100:101], v[100:101], v[172:173] op_sel_hi:[1,0]
	v_pk_mul_f32 v[112:113], v[98:99], v[172:173] op_sel_hi:[1,0]
	v_pk_mul_f32 v[114:115], v[96:97], v[172:173] op_sel_hi:[1,0]
	v_cvt_pk_bf16_f32 v98, v104, v105
	v_cvt_pk_bf16_f32 v96, v108, v109
	v_cvt_pk_bf16_f32 v97, v110, v111
	v_cvt_pk_bf16_f32 v99, v106, v107
	v_cvt_pk_bf16_f32 v100, v100, v101
	v_cvt_pk_bf16_f32 v101, v102, v103
	v_cvt_pk_bf16_f32 v102, v114, v115
	v_cvt_pk_bf16_f32 v103, v112, v113
	v_ashrrev_i32_e32 v177, 31, v176
	s_andn2_b64 s[6:7], exec, s[8:9]
	s_andn2_b64 vcc, exec, s[8:9]
	s_mov_b64 s[8:9], -1
	s_cbranch_vccnz .LBB0_2553
	v_mul_lo_u32 v106, s61, v176
	v_mul_lo_u32 v107, s60, v177
	v_mad_u64_u32 v[104:105], s[8:9], s60, v176, 0
	v_add3_u32 v105, v105, v107, v106
	v_lshl_add_u64 v[104:105], v[104:105], 1, v[174:175]
	s_mov_b64 s[8:9], 0
	global_store_dwordx4 v[104:105], v[96:99], off
	global_store_dwordx4 v[104:105], v[100:103], off offset:64

.LBB0_2996:
	s_andn2_b64 s[4:5], exec, s[8:9]
	s_andn2_b64 vcc, exec, s[8:9]
	v_readfirstlane_b32 s12, v130
	s_cbranch_vccnz .LBB0_3002
	s_ashr_i32 s8, s33, 31
	s_lshr_b32 s8, s8, 29
	s_add_i32 s30, s33, s8
	s_and_b32 s8, s30, -8
	s_sub_i32 s31, s33, s8
	s_cmp_gt_i32 s31, -1
	s_mov_b64 s[8:9], -1
	s_cbranch_scc0 .LBB0_2999
	s_lshl_b32 s34, s31, 5
	s_mov_b64 s[8:9], 0

.LBB0_3028:
	s_mov_b64 s[48:49], -1
	s_andn2_b64 s[6:7], exec, s[54:55]
	s_andn2_b64 vcc, exec, s[54:55]
	v_cvt_f32_ubyte1_e32 v181, v150
	v_cvt_f32_ubyte3_e32 v179, v150
	v_cvt_f32_ubyte2_e32 v178, v150
	v_cvt_f32_ubyte1_e32 v149, v151
	v_cvt_f32_ubyte3_e32 v137, v151
	v_cvt_f32_ubyte2_e32 v136, v151
	v_cvt_f32_ubyte0_e32 v180, v150
	v_cvt_f32_ubyte0_e32 v148, v151
	s_cbranch_vccnz .LBB0_3030
	v_pk_mul_f32 v[150:151], v[180:181], s[28:29] op_sel_hi:[1,0]
	s_lshl_b32 s48, s44, 8
	v_pk_mul_f32 v[150:151], v[96:97], v[150:151]
	s_ashr_i32 s49, s48, 31
	v_cvt_pk_bf16_f32 v182, v150, v151
	v_pk_mul_f32 v[150:151], v[178:179], s[28:29] op_sel_hi:[1,0]
	s_lshl_b32 s12, s64, 1
	v_pk_mul_f32 v[150:151], v[98:99], v[150:151]
	s_nop 0
	v_cvt_pk_bf16_f32 v183, v150, v151
	v_pk_mul_f32 v[150:151], v[148:149], s[28:29] op_sel_hi:[1,0]
	s_nop 0
	v_pk_mul_f32 v[150:151], v[92:93], v[150:151]
	s_nop 0
	v_cvt_pk_bf16_f32 v184, v150, v151
	v_pk_mul_f32 v[150:151], v[136:137], s[28:29] op_sel_hi:[1,0]
	s_nop 0
	v_pk_mul_f32 v[150:151], v[94:95], v[150:151]
	s_nop 0
	v_cvt_pk_bf16_f32 v185, v150, v151
	v_lshl_add_u64 v[150:151], s[48:49], 1, v[176:177]
	v_lshl_add_u64 v[150:151], v[150:151], 0, s[12:13]
	v_lshl_add_u64 v[150:151], v[150:151], 0, v[0:1]
	s_mov_b64 s[48:49], 0
	global_store_dwordx4 v[150:151], v[182:185], off offset:256

.LBB0_3507:
	s_waitcnt lgkmcnt(0)
	s_cmp_lt_i32 s0, 15
	s_cselect_b64 s[2:3], -1, 0
	s_cmp_gt_i32 s1, 14
	s_cselect_b64 s[4:5], -1, 0
	s_and_b64 s[2:3], s[2:3], s[4:5]
	s_andn2_b64 vcc, exec, s[2:3]
	s_cbranch_vccnz .LBB0_3569
	s_load_dword s2, s[92:93], 0x114
	s_load_dwordx2 s[8:9], s[92:93], 0x100
	s_mov_b32 s4, 0x44b00000
	s_mov_b32 s11, 0
	s_mov_b32 s60, s46
	s_waitcnt lgkmcnt(0)
	s_cmp_eq_u32 s2, 12
	s_cselect_b64 s[0:1], -1, 0
	s_cmp_eq_u32 s2, 9
	s_cselect_b64 s[2:3], -1, 0
	s_or_b64 s[2:3], s[0:1], s[2:3]
	s_and_b64 s[2:3], s[2:3], exec
	s_cselect_b32 s33, 2, 1
	s_abs_i32 s2, s46
	v_cvt_f32_u32_e32 v0, s2
	s_sub_i32 s3, 0, s2
	s_ashr_i32 s61, s46, 31
	s_movk_i32 s62, 0xb1
	v_rcp_iflag_f32_e32 v0, v0
	s_mov_b32 s63, 0x3fffe0
	s_mov_b32 s13, s11
	s_mov_b64 s[18:19], 0x80
	v_mul_f32_e32 v0, 0x4f7ffffe, v0
	v_cvt_u32_f32_e32 v0, v0
	s_movk_i32 s66, 0x1600
	v_mov_b32_e32 v207, 1
	v_mov_b64_e32 v[196:197], 0x57f
	v_readfirstlane_b32 s5, v0
	s_mul_i32 s3, s3, s5
	s_mul_hi_u32 s3, s5, s3
	s_add_i32 s5, s5, s3
	s_mul_hi_u32 s3, s5, 0x580
	s_mul_i32 s3, s3, s2
	s_sub_i32 s3, 0x580, s3
	s_sub_i32 s5, s3, s2
	s_cmp_ge_u32 s3, s2
	s_cselect_b32 s3, s5, s3
	s_sub_i32 s5, s3, s2
	s_cmp_ge_u32 s3, s2
	s_cselect_b32 s2, s5, s3
	s_sub_i32 s12, 0x580, s2
	s_lshl_b32 s2, s2, 1
	s_cmp_lg_u32 s2, s46
	s_cselect_b64 s[14:15], -1, 0
	s_cmp_gt_u32 s46, s12
	s_cselect_b64 s[2:3], -1, 0
	s_and_b32 s5, s46, 0xffff
	v_cvt_f32_u32_e32 v1, s5
	s_andn2_b64 s[2:3], exec, s[2:3]
	v_mov_b32_e32 v0, 0
	v_rcp_iflag_f32_e32 v2, v1
	s_mov_b32 s67, 0
	v_mul_f32_e32 v2, 0x44b00000, v2
	v_trunc_f32_e32 v2, v2
	v_cvt_u32_f32_e32 v3, v2
	v_fma_f32 v2, -v2, v1, s4
	v_cmp_ge_f32_e64 s[4:5], |v2|, v1
	s_cmp_lg_u64 s[4:5], 0
	v_readfirstlane_b32 s4, v3
	s_addc_u32 s4, s4, 0
	s_add_i32 s64, 0, 0x23000
	s_xor_b64 s[16:17], s[0:1], -1
	s_and_b32 s65, s4, 0xffff
	s_waitcnt vmcnt(0)
	s_branch .LBB0_3511

.LBB0_3536:
	v_add_u32_e32 v1, 0x10000, v231
	s_waitcnt lgkmcnt(0)
	ds_read_b128 v[180:183], v1
	ds_read_b128 v[184:187], v1 offset:1024
	ds_read_b128 v[188:191], v1 offset:2048
	ds_read_b128 v[192:195], v1 offset:3072
	v_add_u32_e32 v1, 0x14000, v231
	ds_read_b128 v[108:111], v1
	ds_read_b128 v[112:115], v1 offset:1024
	ds_read_b128 v[124:127], v1 offset:2048
	ds_read_b128 v[128:131], v1 offset:3072
	s_andn2_b64 s[6:7], exec, s[52:53]
	s_andn2_b64 vcc, exec, s[52:53]
	s_cbranch_vccnz .LBB0_3538
	ds_read_b128 v[4:7], v233
	ds_read_b128 v[8:11], v233 offset:1024
	ds_read_b128 v[12:15], v233 offset:2048
	ds_read_b128 v[16:19], v233 offset:3072
	ds_read_b128 v[20:23], v233 offset:4096
	ds_read_b128 v[24:27], v233 offset:5120
	ds_read_b128 v[28:31], v233 offset:6144
	ds_read_b128 v[32:35], v233 offset:7168

.LBB0_3540:
	s_barrier
	s_andn2_b64 s[4:5], exec, s[0:1]
	s_andn2_b64 vcc, exec, s[0:1]
	s_cbranch_vccnz .LBB0_3542
	s_waitcnt lgkmcnt(0)
	ds_read_b128 v[4:7], v233 offset:16384
	ds_read_b128 v[8:11], v233 offset:17408
	ds_read_b128 v[12:15], v233 offset:18432
	ds_read_b128 v[16:19], v233 offset:19456
	ds_read_b128 v[20:23], v233 offset:20480
	ds_read_b128 v[24:27], v233 offset:21504
	ds_read_b128 v[28:31], v233 offset:22528
	ds_read_b128 v[32:35], v233 offset:23552

.LBB0_3689:
	s_nop 0
	s_andn2_b64 s[2:3], exec, s[4:5]
	s_andn2_b64 vcc, exec, s[4:5]
	s_mov_b64 s[4:5], s[20:21]
	s_cbranch_vccnz .LBB0_3691
	s_mul_i32 s4, s51, 0x160000
	s_mul_hi_i32 s5, s51, 0x160000
	s_add_u32 s4, s36, s4
	s_addc_u32 s5, s37, s5
